# combined: prologue fp6 item prefetch + first-trip relaxed waits + late gate prefetch on top of LN-in-LDS
# baseline (speedup 1.0000x reference)
.LBB0_171:
	v_and_b32_e32 v3, 48, v0
	v_lshrrev_b32_e32 v2, 4, v178
	v_lshl_or_b32 v3, v193, 6, v3
	v_lshlrev_b32_e32 v4, 3, v193
	s_lshl_b32 s2, s10, 12
	v_lshl_or_b32 v4, v2, 7, v4
	v_bitop3_b32 v5, s2, v3, v1 bitop3:0xf6
	s_lshl_b32 s2, s12, 11
	v_bitop3_b32 v194, s2, v3, v1 bitop3:0xf6
	v_or_b32_e32 v3, s11, v4
	s_lshl_b32 s2, s12, 5
	s_waitcnt vmcnt(4)
	v_or_b32_e32 v195, 0x2000, v3
	v_lshl_or_b32 v3, s10, 11, v4
	s_add_i32 s43, s11, 0
	v_lshl_or_b32 v2, v2, 3, s2
	v_mov_b32_e32 v50, 0
	s_mov_b32 s70, 0
	s_add_i32 s44, s43, 0xe000
	s_add_i32 s45, s43, 0x10000
	s_add_i32 s46, s43, 0x12000
	s_add_i32 s47, s43, 0x14000
	s_add_i32 s48, s43, 0x16000
	s_add_i32 s49, s43, 0x2000
	s_add_i32 s50, s43, 0x6000
	s_add_i32 s51, s43, 0x18000
	s_add_i32 s52, s43, 0x1a000
	s_add_i32 s53, s43, 0x1c000
	s_add_i32 s54, s43, 0x1e000
	s_add_i32 s55, s43, 0xa000
	s_add_i32 s56, s43, 0xd000
	s_add_i32 s57, s43, 0x11000
	s_add_i32 s58, s43, 0x15000
	s_add_i32 s59, s43, 0x1000
	s_add_i32 s60, s43, 0x5000
	s_add_i32 s61, s43, 0x19000
	s_add_i32 s62, s43, 0x1d000
	s_add_i32 s63, s43, 0x9000
	v_or_b32_e32 v196, 0x1400, v2
	s_add_i32 s64, s43, 0xc000
	s_add_i32 s65, s43, 0x4000
	s_add_i32 s66, s43, 0x8000
	s_mov_b32 s24, 0x3b800000
	s_mov_b32 s67, 0xcc00
	v_add_u32_e32 v197, 0, v5
	v_add_u32_e32 v198, 0, v3
	v_mov_b32_e32 v51, v50
	v_mov_b32_e32 v52, v50
	v_mov_b32_e32 v53, v50
	v_mov_b32_e32 v54, v50
	v_mov_b32_e32 v55, v50
	v_mov_b32_e32 v56, v50
	v_mov_b32_e32 v57, v50
	v_mov_b32_e32 v58, v50
	v_mov_b32_e32 v59, v50
	v_mov_b32_e32 v60, v50
	v_mov_b32_e32 v61, v50
	v_mov_b32_e32 v62, v50
	v_mov_b32_e32 v63, v50
	v_mov_b32_e32 v64, v50
	v_mov_b32_e32 v65, v50
	v_mov_b32_e32 v66, v50
	v_mov_b32_e32 v67, v50
	v_mov_b32_e32 v68, v50
	v_mov_b32_e32 v69, v50
	v_mov_b32_e32 v70, v50
	v_mov_b32_e32 v71, v50
	v_mov_b32_e32 v72, v50
	v_mov_b32_e32 v73, v50
	v_mov_b32_e32 v74, v50
	v_mov_b32_e32 v75, v50
	v_mov_b32_e32 v76, v50
	v_mov_b32_e32 v77, v50
	v_mov_b32_e32 v78, v50
	v_mov_b32_e32 v79, v50
	v_mov_b32_e32 v80, v50
	v_mov_b32_e32 v81, v50
	v_mov_b32_e32 v82, v50
	v_mov_b32_e32 v83, v50
	v_mov_b32_e32 v84, v50
	v_mov_b32_e32 v85, v50
	v_mov_b32_e32 v86, v50
	v_mov_b32_e32 v87, v50
	v_mov_b32_e32 v88, v50
	v_mov_b32_e32 v89, v50
	v_mov_b32_e32 v90, v50
	v_mov_b32_e32 v91, v50
	v_mov_b32_e32 v92, v50
	v_mov_b32_e32 v93, v50
	v_mov_b32_e32 v94, v50
	v_mov_b32_e32 v95, v50
	v_mov_b32_e32 v96, v50
	v_mov_b32_e32 v97, v50
	v_mov_b32_e32 v98, v50
	v_mov_b32_e32 v99, v50
	v_mov_b32_e32 v100, v50
	v_mov_b32_e32 v101, v50
	v_mov_b32_e32 v102, v50
	v_mov_b32_e32 v103, v50
	v_mov_b32_e32 v104, v50
	v_mov_b32_e32 v105, v50
	v_mov_b32_e32 v106, v50
	v_mov_b32_e32 v107, v50
	v_mov_b32_e32 v108, v50
	v_mov_b32_e32 v109, v50
	v_mov_b32_e32 v110, v50
	v_mov_b32_e32 v111, v50
	v_mov_b32_e32 v112, v50
	v_mov_b32_e32 v113, v50
	v_mov_b32_e32 v114, v50
	v_mov_b32_e32 v115, v50
	v_mov_b32_e32 v116, v50
	v_mov_b32_e32 v117, v50
	v_mov_b32_e32 v118, v50
	v_mov_b32_e32 v119, v50
	v_mov_b32_e32 v120, v50
	v_mov_b32_e32 v121, v50
	v_mov_b32_e32 v122, v50
	v_mov_b32_e32 v123, v50
	v_mov_b32_e32 v124, v50
	v_mov_b32_e32 v125, v50
	v_mov_b32_e32 v126, v50
	v_mov_b32_e32 v127, v50
	v_mov_b32_e32 v128, v50
	v_mov_b32_e32 v129, v50
	v_mov_b32_e32 v130, v50
	v_mov_b32_e32 v131, v50
	v_mov_b32_e32 v132, v50
	v_mov_b32_e32 v133, v50
	v_mov_b32_e32 v134, v50
	v_mov_b32_e32 v135, v50
	v_mov_b32_e32 v136, v50
	v_mov_b32_e32 v137, v50
	v_mov_b32_e32 v138, v50
	v_mov_b32_e32 v139, v50
	v_mov_b32_e32 v140, v50
	v_mov_b32_e32 v141, v50
	v_mov_b32_e32 v142, v50
	v_mov_b32_e32 v143, v50
	v_mov_b32_e32 v144, v50
	v_mov_b32_e32 v145, v50
	v_mov_b32_e32 v146, v50
	v_mov_b32_e32 v147, v50
	v_mov_b32_e32 v148, v50
	v_mov_b32_e32 v149, v50
	v_mov_b32_e32 v150, v50
	v_mov_b32_e32 v151, v50
	v_mov_b32_e32 v152, v50
	v_mov_b32_e32 v153, v50
	v_mov_b32_e32 v154, v50
	v_mov_b32_e32 v155, v50
	v_mov_b32_e32 v156, v50
	v_mov_b32_e32 v157, v50
	v_mov_b32_e32 v158, v50
	v_mov_b32_e32 v159, v50
	v_mov_b32_e32 v160, v50
	v_mov_b32_e32 v161, v50
	v_mov_b32_e32 v162, v50
	v_mov_b32_e32 v163, v50
	v_mov_b32_e32 v164, v50
	v_mov_b32_e32 v165, v50
	v_mov_b32_e32 v166, v50
	v_mov_b32_e32 v167, v50
	v_mov_b32_e32 v168, v50
	v_mov_b32_e32 v169, v50
	v_mov_b32_e32 v170, v50
	v_mov_b32_e32 v171, v50
	v_mov_b32_e32 v172, v50
	v_mov_b32_e32 v173, v50
	v_mov_b32_e32 v174, v50
	v_mov_b32_e32 v175, v50
	v_mov_b32_e32 v176, v50
	v_mov_b32_e32 v177, v50
	v_lshl_or_b32 v199, s10, 6, v193
	v_mov_b32_e32 v200, 0x7f7f7f7f
	v_mov_b64_e32 v[186:187], 0xa20
	v_mov_b64_e32 v[188:189], 0xa1f
	s_barrier
	s_mov_b32 s32, 1
	s_mov_b32 s84, 0
	v_mov_b32_e32 v244, v180
	v_mov_b32_e32 v245, v182
	v_mov_b32_e32 v246, v184
	s_branch .LBB0_174

.Lsp0_top_L0:
	s_cmp_eq_i32 s73, -2
	s_cselect_b32 s85, s84, 0
	s_add_u32 s34, s2, 0xfffa3000
	s_addc_u32 s35, s3, -1
	s_cmp_eq_u32 s73, 28
	s_cselect_b32 s28, s26, s33
	s_cselect_b32 s29, s27, s72
	s_cselect_b32 s30, s12, s34
	s_cselect_b32 s31, s13, s35
	s_add_u32 s34, s28, 0x60000
	s_addc_u32 s35, s29, 0
	s_mov_b32 m0, s49
	v_mfma_scale_f32_16x16x128_f8f6f4 v[174:177], v[20:25], v[44:49], v[174:177], v200, v200 op_sel_hi:[0,0,0] cbsz:2 blgp:2
	global_load_lds_dwordx4 v246, s[30:31]
	v_mfma_scale_f32_16x16x128_f8f6f4 v[170:173], v[14:19], v[44:49], v[170:173], v200, v200 op_sel_hi:[0,0,0] cbsz:2 blgp:2
	ds_read_b128 v[208:211], v197 offset:16384
	v_mfma_scale_f32_16x16x128_f8f6f4 v[166:169], v[20:25], v[38:43], v[166:169], v200, v200 op_sel_hi:[0,0,0] cbsz:2 blgp:2
	ds_read_b64 v[212:213], v198 offset:24576
	s_mov_b32 m0, s46
	v_mfma_scale_f32_16x16x128_f8f6f4 v[162:165], v[14:19], v[38:43], v[162:165], v200, v200 op_sel_hi:[0,0,0] cbsz:2 blgp:2
	global_load_lds_dwordx4 v246, s[28:29]
	v_mfma_scale_f32_16x16x128_f8f6f4 v[158:161], v[20:25], v[32:37], v[158:161], v200, v200 op_sel_hi:[0,0,0] cbsz:2 blgp:2
	ds_read_b128 v[214:217], v197 offset:17408
	v_mfma_scale_f32_16x16x128_f8f6f4 v[154:157], v[14:19], v[32:37], v[154:157], v200, v200 op_sel_hi:[0,0,0] cbsz:2 blgp:2
	ds_read_b64 v[218:219], v198 offset:25088
	s_mov_b32 m0, s47
	v_mfma_scale_f32_16x16x128_f8f6f4 v[150:153], v[20:25], v[26:31], v[150:153], v200, v200 op_sel_hi:[0,0,0] cbsz:2 blgp:2
	global_load_lds_dwordx4 v244, s[34:35]
	v_mfma_scale_f32_16x16x128_f8f6f4 v[146:149], v[14:19], v[26:31], v[146:149], v200, v200 op_sel_hi:[0,0,0] cbsz:2 blgp:2
	ds_read_b128 v[220:223], v197 offset:18432
	v_mfma_scale_f32_16x16x128_f8f6f4 v[142:145], v[8:13], v[44:49], v[142:145], v200, v200 op_sel_hi:[0,0,0] cbsz:2 blgp:2
	ds_read_b64 v[224:225], v198 offset:25600
	s_mov_b32 m0, s58
	v_mfma_scale_f32_16x16x128_f8f6f4 v[138:141], v[2:7], v[44:49], v[138:141], v200, v200 op_sel_hi:[0,0,0] cbsz:2 blgp:2
	global_load_lds_dwordx4 v245, s[34:35]
	v_mfma_scale_f32_16x16x128_f8f6f4 v[134:137], v[8:13], v[38:43], v[134:137], v200, v200 op_sel_hi:[0,0,0] cbsz:2 blgp:2
	ds_read_b128 v[226:229], v197 offset:19456
	v_mfma_scale_f32_16x16x128_f8f6f4 v[130:133], v[2:7], v[38:43], v[130:133], v200, v200 op_sel_hi:[0,0,0] cbsz:2 blgp:2
	ds_read_b64 v[230:231], v198 offset:26112
	v_mfma_scale_f32_16x16x128_f8f6f4 v[126:129], v[8:13], v[32:37], v[126:129], v200, v200 op_sel_hi:[0,0,0] cbsz:2 blgp:2
	v_mfma_scale_f32_16x16x128_f8f6f4 v[122:125], v[2:7], v[32:37], v[122:125], v200, v200 op_sel_hi:[0,0,0] cbsz:2 blgp:2
	v_mfma_scale_f32_16x16x128_f8f6f4 v[118:121], v[8:13], v[26:31], v[118:121], v200, v200 op_sel_hi:[0,0,0] cbsz:2 blgp:2
	v_mfma_scale_f32_16x16x128_f8f6f4 v[114:117], v[2:7], v[26:31], v[114:117], v200, v200 op_sel_hi:[0,0,0] cbsz:2 blgp:2
	s_cmp_eq_u32 s85, 1
	s_cbranch_scc1 .Lsp0_fw1_L0
	s_waitcnt vmcnt(6)
	s_branch .Lsp0_fj1_L0
.Lsp0_fw1_L0:
	s_waitcnt vmcnt(22)
.Lsp0_fj1_L0:
	s_waitcnt lgkmcnt(0)
	s_barrier
	s_add_u32 s34, s30, 0x60000
	s_addc_u32 s35, s31, 0
	s_mov_b32 m0, s65
	v_mfma_scale_f32_16x16x128_f8f6f4 v[110:113], v[20:25], v[208:213], v[110:113], v200, v200 op_sel_hi:[0,0,0] cbsz:2 blgp:2
	global_load_lds_dwordx4 v244, s[34:35]
	ds_read_b128 v[44:47], v197 offset:32768
	s_mov_b32 m0, s60
	v_mfma_scale_f32_16x16x128_f8f6f4 v[106:109], v[14:19], v[208:213], v[106:109], v200, v200 op_sel_hi:[0,0,0] cbsz:2 blgp:2
	ds_read_b64 v[48:49], v198 offset:40960
	global_load_lds_dwordx4 v245, s[34:35]
	v_mfma_scale_f32_16x16x128_f8f6f4 v[102:105], v[20:25], v[214:219], v[102:105], v200, v200 op_sel_hi:[0,0,0] cbsz:2 blgp:2
	ds_read_b128 v[38:41], v197 offset:33792
	ds_read_b64 v[42:43], v198 offset:41472
	v_mfma_scale_f32_16x16x128_f8f6f4 v[98:101], v[14:19], v[214:219], v[98:101], v200, v200 op_sel_hi:[0,0,0] cbsz:2 blgp:2
	ds_read_b128 v[32:35], v197 offset:34816
	ds_read_b64 v[36:37], v198 offset:41984
	v_mfma_scale_f32_16x16x128_f8f6f4 v[94:97], v[20:25], v[220:225], v[94:97], v200, v200 op_sel_hi:[0,0,0] cbsz:2 blgp:2
	ds_read_b128 v[26:29], v197 offset:35840
	ds_read_b64 v[30:31], v198 offset:42496
	v_mfma_scale_f32_16x16x128_f8f6f4 v[90:93], v[14:19], v[220:225], v[90:93], v200, v200 op_sel_hi:[0,0,0] cbsz:2 blgp:2
	ds_read_b128 v[232:235], v247 offset:32768
	ds_read_b64 v[236:237], v248 offset:32768
	v_mfma_scale_f32_16x16x128_f8f6f4 v[86:89], v[20:25], v[226:231], v[86:89], v200, v200 op_sel_hi:[0,0,0] cbsz:2 blgp:2
	ds_read_b128 v[238:241], v247 offset:33792
	ds_read_b64 v[242:243], v248 offset:33280
	v_mfma_scale_f32_16x16x128_f8f6f4 v[82:85], v[14:19], v[226:231], v[82:85], v200, v200 op_sel_hi:[0,0,0] cbsz:2 blgp:2
	ds_read_b128 v[180:183], v247 offset:49152
	ds_read_b64 v[184:185], v248 offset:49152
	v_mfma_scale_f32_16x16x128_f8f6f4 v[78:81], v[8:13], v[208:213], v[78:81], v200, v200 op_sel_hi:[0,0,0] cbsz:2 blgp:2
	ds_read_b128 v[250:253], v247 offset:50176
	ds_read_b64 v[254:255], v248 offset:49664
	v_mfma_scale_f32_16x16x128_f8f6f4 v[74:77], v[2:7], v[208:213], v[74:77], v200, v200 op_sel_hi:[0,0,0] cbsz:2 blgp:2
	v_mfma_scale_f32_16x16x128_f8f6f4 v[70:73], v[8:13], v[214:219], v[70:73], v200, v200 op_sel_hi:[0,0,0] cbsz:2 blgp:2
	v_mfma_scale_f32_16x16x128_f8f6f4 v[66:69], v[2:7], v[214:219], v[66:69], v200, v200 op_sel_hi:[0,0,0] cbsz:2 blgp:2
	v_mfma_scale_f32_16x16x128_f8f6f4 v[62:65], v[8:13], v[220:225], v[62:65], v200, v200 op_sel_hi:[0,0,0] cbsz:2 blgp:2
	v_mfma_scale_f32_16x16x128_f8f6f4 v[58:61], v[2:7], v[220:225], v[58:61], v200, v200 op_sel_hi:[0,0,0] cbsz:2 blgp:2
	v_mfma_scale_f32_16x16x128_f8f6f4 v[54:57], v[8:13], v[226:231], v[54:57], v200, v200 op_sel_hi:[0,0,0] cbsz:2 blgp:2
	v_mfma_scale_f32_16x16x128_f8f6f4 v[50:53], v[2:7], v[226:231], v[50:53], v200, v200 op_sel_hi:[0,0,0] cbsz:2 blgp:2
	s_cmp_eq_u32 s85, 1
	s_cbranch_scc1 .Lsp0_fw2_L0
	s_waitcnt vmcnt(6)
	s_branch .Lsp0_fj2_L0

.Lsp0_fj2_L0:
	s_waitcnt lgkmcnt(0)
	s_barrier
	s_add_u32 s30, s30, 0x3000
	s_addc_u32 s31, s31, 0
	s_add_u32 s28, s28, 0x3000
	s_addc_u32 s29, s29, 0
	s_add_u32 s34, s28, 0x60000
	s_addc_u32 s35, s29, 0
	s_mov_b32 m0, s55
	v_mfma_scale_f32_16x16x128_f8f6f4 v[174:177], v[232:237], v[44:49], v[174:177], v200, v200 op_sel_hi:[0,0,0] cbsz:2 blgp:2
	global_load_lds_dwordx4 v246, s[30:31]
	v_mfma_scale_f32_16x16x128_f8f6f4 v[170:173], v[238:243], v[44:49], v[170:173], v200, v200 op_sel_hi:[0,0,0] cbsz:2 blgp:2
	ds_read_b128 v[208:211], v197 offset:49152
	v_mfma_scale_f32_16x16x128_f8f6f4 v[166:169], v[232:237], v[38:43], v[166:169], v200, v200 op_sel_hi:[0,0,0] cbsz:2 blgp:2
	ds_read_b64 v[212:213], v198 offset:57344
	s_mov_b32 m0, s52
	v_mfma_scale_f32_16x16x128_f8f6f4 v[162:165], v[238:243], v[38:43], v[162:165], v200, v200 op_sel_hi:[0,0,0] cbsz:2 blgp:2
	global_load_lds_dwordx4 v246, s[28:29]
	v_mfma_scale_f32_16x16x128_f8f6f4 v[158:161], v[232:237], v[32:37], v[158:161], v200, v200 op_sel_hi:[0,0,0] cbsz:2 blgp:2
	ds_read_b128 v[214:217], v197 offset:50176
	v_mfma_scale_f32_16x16x128_f8f6f4 v[154:157], v[238:243], v[32:37], v[154:157], v200, v200 op_sel_hi:[0,0,0] cbsz:2 blgp:2
	ds_read_b64 v[218:219], v198 offset:57856
	s_mov_b32 m0, s53
	v_mfma_scale_f32_16x16x128_f8f6f4 v[150:153], v[232:237], v[26:31], v[150:153], v200, v200 op_sel_hi:[0,0,0] cbsz:2 blgp:2
	global_load_lds_dwordx4 v244, s[34:35]
	v_mfma_scale_f32_16x16x128_f8f6f4 v[146:149], v[238:243], v[26:31], v[146:149], v200, v200 op_sel_hi:[0,0,0] cbsz:2 blgp:2
	ds_read_b128 v[220:223], v197 offset:51200
	v_mfma_scale_f32_16x16x128_f8f6f4 v[142:145], v[180:185], v[44:49], v[142:145], v200, v200 op_sel_hi:[0,0,0] cbsz:2 blgp:2
	ds_read_b64 v[224:225], v198 offset:58368
	s_mov_b32 m0, s62
	v_mfma_scale_f32_16x16x128_f8f6f4 v[138:141], v[250:255], v[44:49], v[138:141], v200, v200 op_sel_hi:[0,0,0] cbsz:2 blgp:2
	global_load_lds_dwordx4 v245, s[34:35]
	v_mfma_scale_f32_16x16x128_f8f6f4 v[134:137], v[180:185], v[38:43], v[134:137], v200, v200 op_sel_hi:[0,0,0] cbsz:2 blgp:2
	ds_read_b128 v[226:229], v197 offset:52224
	v_mfma_scale_f32_16x16x128_f8f6f4 v[130:133], v[250:255], v[38:43], v[130:133], v200, v200 op_sel_hi:[0,0,0] cbsz:2 blgp:2
	ds_read_b64 v[230:231], v198 offset:58880
	v_mfma_scale_f32_16x16x128_f8f6f4 v[126:129], v[180:185], v[32:37], v[126:129], v200, v200 op_sel_hi:[0,0,0] cbsz:2 blgp:2
	v_mfma_scale_f32_16x16x128_f8f6f4 v[122:125], v[250:255], v[32:37], v[122:125], v200, v200 op_sel_hi:[0,0,0] cbsz:2 blgp:2
	v_mfma_scale_f32_16x16x128_f8f6f4 v[118:121], v[180:185], v[26:31], v[118:121], v200, v200 op_sel_hi:[0,0,0] cbsz:2 blgp:2
	v_mfma_scale_f32_16x16x128_f8f6f4 v[114:117], v[250:255], v[26:31], v[114:117], v200, v200 op_sel_hi:[0,0,0] cbsz:2 blgp:2
	s_waitcnt vmcnt(6)
	s_waitcnt lgkmcnt(0)
	s_barrier
	s_add_u32 s34, s30, 0x60000
	s_addc_u32 s35, s31, 0
	s_mov_b32 m0, s64
	v_mfma_scale_f32_16x16x128_f8f6f4 v[110:113], v[232:237], v[208:213], v[110:113], v200, v200 op_sel_hi:[0,0,0] cbsz:2 blgp:2
	global_load_lds_dwordx4 v244, s[34:35]
	ds_read_b128 v[44:47], v197
	s_mov_b32 m0, s56
	v_mfma_scale_f32_16x16x128_f8f6f4 v[106:109], v[238:243], v[208:213], v[106:109], v200, v200 op_sel_hi:[0,0,0] cbsz:2 blgp:2
	ds_read_b64 v[48:49], v198 offset:8192
	global_load_lds_dwordx4 v245, s[34:35]
	v_mfma_scale_f32_16x16x128_f8f6f4 v[102:105], v[232:237], v[214:219], v[102:105], v200, v200 op_sel_hi:[0,0,0] cbsz:2 blgp:2
	ds_read_b128 v[38:41], v197 offset:1024
	ds_read_b64 v[42:43], v198 offset:8704
	v_mfma_scale_f32_16x16x128_f8f6f4 v[98:101], v[238:243], v[214:219], v[98:101], v200, v200 op_sel_hi:[0,0,0] cbsz:2 blgp:2
	ds_read_b128 v[32:35], v197 offset:2048
	ds_read_b64 v[36:37], v198 offset:9216
	v_mfma_scale_f32_16x16x128_f8f6f4 v[94:97], v[232:237], v[220:225], v[94:97], v200, v200 op_sel_hi:[0,0,0] cbsz:2 blgp:2
	ds_read_b128 v[26:29], v197 offset:3072
	ds_read_b64 v[30:31], v198 offset:9728
	v_mfma_scale_f32_16x16x128_f8f6f4 v[90:93], v[238:243], v[220:225], v[90:93], v200, v200 op_sel_hi:[0,0,0] cbsz:2 blgp:2
	ds_read_b128 v[20:23], v247
	ds_read_b64 v[24:25], v248
	v_mfma_scale_f32_16x16x128_f8f6f4 v[86:89], v[232:237], v[226:231], v[86:89], v200, v200 op_sel_hi:[0,0,0] cbsz:2 blgp:2
	ds_read_b128 v[14:17], v247 offset:1024
	ds_read_b64 v[18:19], v248 offset:512
	v_mfma_scale_f32_16x16x128_f8f6f4 v[82:85], v[238:243], v[226:231], v[82:85], v200, v200 op_sel_hi:[0,0,0] cbsz:2 blgp:2
	ds_read_b128 v[8:11], v247 offset:16384
	ds_read_b64 v[12:13], v248 offset:16384
	v_mfma_scale_f32_16x16x128_f8f6f4 v[78:81], v[180:185], v[208:213], v[78:81], v200, v200 op_sel_hi:[0,0,0] cbsz:2 blgp:2
	ds_read_b128 v[2:5], v247 offset:17408
	ds_read_b64 v[6:7], v248 offset:16896
	v_mfma_scale_f32_16x16x128_f8f6f4 v[74:77], v[250:255], v[208:213], v[74:77], v200, v200 op_sel_hi:[0,0,0] cbsz:2 blgp:2
	v_mfma_scale_f32_16x16x128_f8f6f4 v[70:73], v[180:185], v[214:219], v[70:73], v200, v200 op_sel_hi:[0,0,0] cbsz:2 blgp:2
	v_mfma_scale_f32_16x16x128_f8f6f4 v[66:69], v[250:255], v[214:219], v[66:69], v200, v200 op_sel_hi:[0,0,0] cbsz:2 blgp:2
	v_mfma_scale_f32_16x16x128_f8f6f4 v[62:65], v[180:185], v[220:225], v[62:65], v200, v200 op_sel_hi:[0,0,0] cbsz:2 blgp:2
	v_mfma_scale_f32_16x16x128_f8f6f4 v[58:61], v[250:255], v[220:225], v[58:61], v200, v200 op_sel_hi:[0,0,0] cbsz:2 blgp:2
	v_mfma_scale_f32_16x16x128_f8f6f4 v[54:57], v[180:185], v[226:231], v[54:57], v200, v200 op_sel_hi:[0,0,0] cbsz:2 blgp:2
	v_mfma_scale_f32_16x16x128_f8f6f4 v[50:53], v[250:255], v[226:231], v[50:53], v200, v200 op_sel_hi:[0,0,0] cbsz:2 blgp:2
	s_waitcnt vmcnt(6)
	s_waitcnt lgkmcnt(0)
	s_barrier
	s_add_i32 s73, s73, 2
	s_add_u32 s2, s2, 0x6000
	s_addc_u32 s3, s3, 0
	s_add_u32 s33, s33, 0x6000
	s_addc_u32 s72, s72, 0
	s_cmp_gt_u32 s73, 29
	s_cbranch_scc0 .Lsp0_top_L0
	s_mov_b32 s84, 1
	s_branch .LBB0_198

.Lsp1_top_L0:
	s_cmp_eq_i32 s73, -2
	s_cselect_b32 s85, s84, 0
	s_add_u32 s34, s2, 0xfffa3000
	s_addc_u32 s35, s3, -1
	s_cmp_eq_u32 s73, 28
	s_cselect_b32 s28, s26, s33
	s_cselect_b32 s29, s27, s72
	s_cselect_b32 s30, s12, s34
	s_cselect_b32 s31, s13, s35
	s_add_u32 s34, s28, 0x60000
	s_addc_u32 s35, s29, 0
	s_mov_b32 m0, s43
	v_mfma_scale_f32_16x16x128_f8f6f4 v[174:177], v[20:25], v[44:49], v[174:177], v200, v200 op_sel_hi:[0,0,0] cbsz:2 blgp:2
	global_load_lds_dwordx4 v244, s[30:31]
	v_mfma_scale_f32_16x16x128_f8f6f4 v[170:173], v[14:19], v[44:49], v[170:173], v200, v200 op_sel_hi:[0,0,0] cbsz:2 blgp:2
	ds_read_b128 v[208:211], v197 offset:16384
	v_mfma_scale_f32_16x16x128_f8f6f4 v[166:169], v[20:25], v[38:43], v[166:169], v200, v200 op_sel_hi:[0,0,0] cbsz:2 blgp:2
	ds_read_b64 v[212:213], v198 offset:24576
	s_mov_b32 m0, s59
	v_mfma_scale_f32_16x16x128_f8f6f4 v[162:165], v[14:19], v[38:43], v[162:165], v200, v200 op_sel_hi:[0,0,0] cbsz:2 blgp:2
	global_load_lds_dwordx4 v245, s[30:31]
	v_mfma_scale_f32_16x16x128_f8f6f4 v[158:161], v[20:25], v[32:37], v[158:161], v200, v200 op_sel_hi:[0,0,0] cbsz:2 blgp:2
	ds_read_b128 v[214:217], v197 offset:17408
	v_mfma_scale_f32_16x16x128_f8f6f4 v[154:157], v[14:19], v[32:37], v[154:157], v200, v200 op_sel_hi:[0,0,0] cbsz:2 blgp:2
	ds_read_b64 v[218:219], v198 offset:25088
	s_mov_b32 m0, s45
	v_mfma_scale_f32_16x16x128_f8f6f4 v[150:153], v[20:25], v[26:31], v[150:153], v200, v200 op_sel_hi:[0,0,0] cbsz:2 blgp:2
	global_load_lds_dwordx4 v244, s[28:29]
	v_mfma_scale_f32_16x16x128_f8f6f4 v[146:149], v[14:19], v[26:31], v[146:149], v200, v200 op_sel_hi:[0,0,0] cbsz:2 blgp:2
	ds_read_b128 v[220:223], v197 offset:18432
	v_mfma_scale_f32_16x16x128_f8f6f4 v[142:145], v[8:13], v[44:49], v[142:145], v200, v200 op_sel_hi:[0,0,0] cbsz:2 blgp:2
	ds_read_b64 v[224:225], v198 offset:25600
	s_mov_b32 m0, s57
	v_mfma_scale_f32_16x16x128_f8f6f4 v[138:141], v[2:7], v[44:49], v[138:141], v200, v200 op_sel_hi:[0,0,0] cbsz:2 blgp:2
	global_load_lds_dwordx4 v245, s[28:29]
	v_mfma_scale_f32_16x16x128_f8f6f4 v[134:137], v[8:13], v[38:43], v[134:137], v200, v200 op_sel_hi:[0,0,0] cbsz:2 blgp:2
	ds_read_b128 v[226:229], v197 offset:19456
	v_mfma_scale_f32_16x16x128_f8f6f4 v[130:133], v[2:7], v[38:43], v[130:133], v200, v200 op_sel_hi:[0,0,0] cbsz:2 blgp:2
	ds_read_b64 v[230:231], v198 offset:26112
	s_mov_b32 m0, s48
	v_mfma_scale_f32_16x16x128_f8f6f4 v[126:129], v[8:13], v[32:37], v[126:129], v200, v200 op_sel_hi:[0,0,0] cbsz:2 blgp:2
	global_load_lds_dwordx4 v246, s[34:35]
	v_mfma_scale_f32_16x16x128_f8f6f4 v[122:125], v[2:7], v[32:37], v[122:125], v200, v200 op_sel_hi:[0,0,0] cbsz:2 blgp:2
	v_mfma_scale_f32_16x16x128_f8f6f4 v[118:121], v[8:13], v[26:31], v[118:121], v200, v200 op_sel_hi:[0,0,0] cbsz:2 blgp:2
	v_mfma_scale_f32_16x16x128_f8f6f4 v[114:117], v[2:7], v[26:31], v[114:117], v200, v200 op_sel_hi:[0,0,0] cbsz:2 blgp:2
	s_cmp_eq_u32 s85, 1
	s_cbranch_scc1 .Lsp1_fw1_L0
	s_waitcnt vmcnt(6)
	s_branch .Lsp1_fj1_L0

.Lsp1_fj1_L0:
	s_waitcnt lgkmcnt(0)
	s_barrier
	s_add_u32 s34, s30, 0x60000
	s_addc_u32 s35, s31, 0
	s_mov_b32 m0, s50
	v_mfma_scale_f32_16x16x128_f8f6f4 v[110:113], v[20:25], v[208:213], v[110:113], v200, v200 op_sel_hi:[0,0,0] cbsz:2 blgp:2
	global_load_lds_dwordx4 v246, s[34:35]
	ds_read_b128 v[44:47], v197 offset:32768
	v_mfma_scale_f32_16x16x128_f8f6f4 v[106:109], v[14:19], v[208:213], v[106:109], v200, v200 op_sel_hi:[0,0,0] cbsz:2 blgp:2
	ds_read_b64 v[48:49], v198 offset:40960
	ds_read_b128 v[38:41], v197 offset:33792
	v_mfma_scale_f32_16x16x128_f8f6f4 v[102:105], v[20:25], v[214:219], v[102:105], v200, v200 op_sel_hi:[0,0,0] cbsz:2 blgp:2
	ds_read_b64 v[42:43], v198 offset:41472
	ds_read_b128 v[32:35], v197 offset:34816
	v_mfma_scale_f32_16x16x128_f8f6f4 v[98:101], v[14:19], v[214:219], v[98:101], v200, v200 op_sel_hi:[0,0,0] cbsz:2 blgp:2
	ds_read_b64 v[36:37], v198 offset:41984
	ds_read_b128 v[26:29], v197 offset:35840
	v_mfma_scale_f32_16x16x128_f8f6f4 v[94:97], v[20:25], v[220:225], v[94:97], v200, v200 op_sel_hi:[0,0,0] cbsz:2 blgp:2
	ds_read_b64 v[30:31], v198 offset:42496
	ds_read_b128 v[232:235], v247 offset:32768
	v_mfma_scale_f32_16x16x128_f8f6f4 v[90:93], v[14:19], v[220:225], v[90:93], v200, v200 op_sel_hi:[0,0,0] cbsz:2 blgp:2
	ds_read_b64 v[236:237], v248 offset:32768
	ds_read_b128 v[238:241], v247 offset:33792
	v_mfma_scale_f32_16x16x128_f8f6f4 v[86:89], v[20:25], v[226:231], v[86:89], v200, v200 op_sel_hi:[0,0,0] cbsz:2 blgp:2
	ds_read_b64 v[242:243], v248 offset:33280
	ds_read_b128 v[180:183], v247 offset:49152
	v_mfma_scale_f32_16x16x128_f8f6f4 v[82:85], v[14:19], v[226:231], v[82:85], v200, v200 op_sel_hi:[0,0,0] cbsz:2 blgp:2
	ds_read_b64 v[184:185], v248 offset:49152
	ds_read_b128 v[250:253], v247 offset:50176
	v_mfma_scale_f32_16x16x128_f8f6f4 v[78:81], v[8:13], v[208:213], v[78:81], v200, v200 op_sel_hi:[0,0,0] cbsz:2 blgp:2
	ds_read_b64 v[254:255], v248 offset:49664
	v_mfma_scale_f32_16x16x128_f8f6f4 v[74:77], v[2:7], v[208:213], v[74:77], v200, v200 op_sel_hi:[0,0,0] cbsz:2 blgp:2
	v_mfma_scale_f32_16x16x128_f8f6f4 v[70:73], v[8:13], v[214:219], v[70:73], v200, v200 op_sel_hi:[0,0,0] cbsz:2 blgp:2
	v_mfma_scale_f32_16x16x128_f8f6f4 v[66:69], v[2:7], v[214:219], v[66:69], v200, v200 op_sel_hi:[0,0,0] cbsz:2 blgp:2
	v_mfma_scale_f32_16x16x128_f8f6f4 v[62:65], v[8:13], v[220:225], v[62:65], v200, v200 op_sel_hi:[0,0,0] cbsz:2 blgp:2
	v_mfma_scale_f32_16x16x128_f8f6f4 v[58:61], v[2:7], v[220:225], v[58:61], v200, v200 op_sel_hi:[0,0,0] cbsz:2 blgp:2
	v_mfma_scale_f32_16x16x128_f8f6f4 v[54:57], v[8:13], v[226:231], v[54:57], v200, v200 op_sel_hi:[0,0,0] cbsz:2 blgp:2
	v_mfma_scale_f32_16x16x128_f8f6f4 v[50:53], v[2:7], v[226:231], v[50:53], v200, v200 op_sel_hi:[0,0,0] cbsz:2 blgp:2
	s_cmp_eq_u32 s85, 1
	s_cbranch_scc1 .Lsp1_fw2_L0
	s_waitcnt vmcnt(6)
	s_branch .Lsp1_fj2_L0

.Lsp1_fj2_L0:
	s_waitcnt lgkmcnt(0)
	s_barrier
	s_add_u32 s30, s30, 0x3000
	s_addc_u32 s31, s31, 0
	s_add_u32 s28, s28, 0x3000
	s_addc_u32 s29, s29, 0
	s_add_u32 s34, s28, 0x60000
	s_addc_u32 s35, s29, 0
	s_mov_b32 m0, s66
	v_mfma_scale_f32_16x16x128_f8f6f4 v[174:177], v[232:237], v[44:49], v[174:177], v200, v200 op_sel_hi:[0,0,0] cbsz:2 blgp:2
	global_load_lds_dwordx4 v244, s[30:31]
	v_mfma_scale_f32_16x16x128_f8f6f4 v[170:173], v[238:243], v[44:49], v[170:173], v200, v200 op_sel_hi:[0,0,0] cbsz:2 blgp:2
	ds_read_b128 v[208:211], v197 offset:49152
	v_mfma_scale_f32_16x16x128_f8f6f4 v[166:169], v[232:237], v[38:43], v[166:169], v200, v200 op_sel_hi:[0,0,0] cbsz:2 blgp:2
	ds_read_b64 v[212:213], v198 offset:57344
	s_mov_b32 m0, s63
	v_mfma_scale_f32_16x16x128_f8f6f4 v[162:165], v[238:243], v[38:43], v[162:165], v200, v200 op_sel_hi:[0,0,0] cbsz:2 blgp:2
	global_load_lds_dwordx4 v245, s[30:31]
	v_mfma_scale_f32_16x16x128_f8f6f4 v[158:161], v[232:237], v[32:37], v[158:161], v200, v200 op_sel_hi:[0,0,0] cbsz:2 blgp:2
	ds_read_b128 v[214:217], v197 offset:50176
	v_mfma_scale_f32_16x16x128_f8f6f4 v[154:157], v[238:243], v[32:37], v[154:157], v200, v200 op_sel_hi:[0,0,0] cbsz:2 blgp:2
	ds_read_b64 v[218:219], v198 offset:57856
	s_mov_b32 m0, s51
	v_mfma_scale_f32_16x16x128_f8f6f4 v[150:153], v[232:237], v[26:31], v[150:153], v200, v200 op_sel_hi:[0,0,0] cbsz:2 blgp:2
	global_load_lds_dwordx4 v244, s[28:29]
	v_mfma_scale_f32_16x16x128_f8f6f4 v[146:149], v[238:243], v[26:31], v[146:149], v200, v200 op_sel_hi:[0,0,0] cbsz:2 blgp:2
	ds_read_b128 v[220:223], v197 offset:51200
	v_mfma_scale_f32_16x16x128_f8f6f4 v[142:145], v[180:185], v[44:49], v[142:145], v200, v200 op_sel_hi:[0,0,0] cbsz:2 blgp:2
	ds_read_b64 v[224:225], v198 offset:58368
	s_mov_b32 m0, s61
	v_mfma_scale_f32_16x16x128_f8f6f4 v[138:141], v[250:255], v[44:49], v[138:141], v200, v200 op_sel_hi:[0,0,0] cbsz:2 blgp:2
	global_load_lds_dwordx4 v245, s[28:29]
	v_mfma_scale_f32_16x16x128_f8f6f4 v[134:137], v[180:185], v[38:43], v[134:137], v200, v200 op_sel_hi:[0,0,0] cbsz:2 blgp:2
	ds_read_b128 v[226:229], v197 offset:52224
	v_mfma_scale_f32_16x16x128_f8f6f4 v[130:133], v[250:255], v[38:43], v[130:133], v200, v200 op_sel_hi:[0,0,0] cbsz:2 blgp:2
	ds_read_b64 v[230:231], v198 offset:58880
	s_mov_b32 m0, s54
	v_mfma_scale_f32_16x16x128_f8f6f4 v[126:129], v[180:185], v[32:37], v[126:129], v200, v200 op_sel_hi:[0,0,0] cbsz:2 blgp:2
	global_load_lds_dwordx4 v246, s[34:35]
	v_mfma_scale_f32_16x16x128_f8f6f4 v[122:125], v[250:255], v[32:37], v[122:125], v200, v200 op_sel_hi:[0,0,0] cbsz:2 blgp:2
	v_mfma_scale_f32_16x16x128_f8f6f4 v[118:121], v[180:185], v[26:31], v[118:121], v200, v200 op_sel_hi:[0,0,0] cbsz:2 blgp:2
	v_mfma_scale_f32_16x16x128_f8f6f4 v[114:117], v[250:255], v[26:31], v[114:117], v200, v200 op_sel_hi:[0,0,0] cbsz:2 blgp:2
	s_waitcnt vmcnt(6)
	s_waitcnt lgkmcnt(0)
	s_barrier
	s_add_u32 s34, s30, 0x60000
	s_addc_u32 s35, s31, 0
	s_mov_b32 m0, s44
	v_mfma_scale_f32_16x16x128_f8f6f4 v[110:113], v[232:237], v[208:213], v[110:113], v200, v200 op_sel_hi:[0,0,0] cbsz:2 blgp:2
	global_load_lds_dwordx4 v246, s[34:35]
	ds_read_b128 v[44:47], v197
	v_mfma_scale_f32_16x16x128_f8f6f4 v[106:109], v[238:243], v[208:213], v[106:109], v200, v200 op_sel_hi:[0,0,0] cbsz:2 blgp:2
	ds_read_b64 v[48:49], v198 offset:8192
	ds_read_b128 v[38:41], v197 offset:1024
	v_mfma_scale_f32_16x16x128_f8f6f4 v[102:105], v[232:237], v[214:219], v[102:105], v200, v200 op_sel_hi:[0,0,0] cbsz:2 blgp:2
	ds_read_b64 v[42:43], v198 offset:8704
	ds_read_b128 v[32:35], v197 offset:2048
	v_mfma_scale_f32_16x16x128_f8f6f4 v[98:101], v[238:243], v[214:219], v[98:101], v200, v200 op_sel_hi:[0,0,0] cbsz:2 blgp:2
	ds_read_b64 v[36:37], v198 offset:9216
	ds_read_b128 v[26:29], v197 offset:3072
	v_mfma_scale_f32_16x16x128_f8f6f4 v[94:97], v[232:237], v[220:225], v[94:97], v200, v200 op_sel_hi:[0,0,0] cbsz:2 blgp:2
	ds_read_b64 v[30:31], v198 offset:9728
	ds_read_b128 v[20:23], v247
	v_mfma_scale_f32_16x16x128_f8f6f4 v[90:93], v[238:243], v[220:225], v[90:93], v200, v200 op_sel_hi:[0,0,0] cbsz:2 blgp:2
	ds_read_b64 v[24:25], v248
	ds_read_b128 v[14:17], v247 offset:1024
	v_mfma_scale_f32_16x16x128_f8f6f4 v[86:89], v[232:237], v[226:231], v[86:89], v200, v200 op_sel_hi:[0,0,0] cbsz:2 blgp:2
	ds_read_b64 v[18:19], v248 offset:512
	ds_read_b128 v[8:11], v247 offset:16384
	v_mfma_scale_f32_16x16x128_f8f6f4 v[82:85], v[238:243], v[226:231], v[82:85], v200, v200 op_sel_hi:[0,0,0] cbsz:2 blgp:2
	ds_read_b64 v[12:13], v248 offset:16384
	ds_read_b128 v[2:5], v247 offset:17408
	v_mfma_scale_f32_16x16x128_f8f6f4 v[78:81], v[180:185], v[208:213], v[78:81], v200, v200 op_sel_hi:[0,0,0] cbsz:2 blgp:2
	ds_read_b64 v[6:7], v248 offset:16896
	v_mfma_scale_f32_16x16x128_f8f6f4 v[74:77], v[250:255], v[208:213], v[74:77], v200, v200 op_sel_hi:[0,0,0] cbsz:2 blgp:2
	v_mfma_scale_f32_16x16x128_f8f6f4 v[70:73], v[180:185], v[214:219], v[70:73], v200, v200 op_sel_hi:[0,0,0] cbsz:2 blgp:2
	v_mfma_scale_f32_16x16x128_f8f6f4 v[66:69], v[250:255], v[214:219], v[66:69], v200, v200 op_sel_hi:[0,0,0] cbsz:2 blgp:2
	v_mfma_scale_f32_16x16x128_f8f6f4 v[62:65], v[180:185], v[220:225], v[62:65], v200, v200 op_sel_hi:[0,0,0] cbsz:2 blgp:2
	v_mfma_scale_f32_16x16x128_f8f6f4 v[58:61], v[250:255], v[220:225], v[58:61], v200, v200 op_sel_hi:[0,0,0] cbsz:2 blgp:2
	v_mfma_scale_f32_16x16x128_f8f6f4 v[54:57], v[180:185], v[226:231], v[54:57], v200, v200 op_sel_hi:[0,0,0] cbsz:2 blgp:2
	v_mfma_scale_f32_16x16x128_f8f6f4 v[50:53], v[250:255], v[226:231], v[50:53], v200, v200 op_sel_hi:[0,0,0] cbsz:2 blgp:2
	s_waitcnt vmcnt(6)
	s_waitcnt lgkmcnt(0)
	s_barrier
	s_add_i32 s73, s73, 2
	s_add_u32 s2, s2, 0x6000
	s_addc_u32 s3, s3, 0
	s_add_u32 s33, s33, 0x6000
	s_addc_u32 s72, s72, 0
	s_cmp_gt_u32 s73, 29
	s_cbranch_scc0 .Lsp1_top_L0
	s_mov_b32 s84, 1
	s_branch .LBB0_198

.Lg16_pf_g0:
	s_lshr_b32 s64, s58, 3
	s_lshl_b32 s64, s64, 13
	s_add_u32 s84, s19, s64
	s_addc_u32 s85, s55, 0
.Lg16_p_g0:
	s_cmp_eq_u32 s58, 31
	s_cselect_b32 s22, s52, s60
	s_cselect_b32 s23, s11, s61
	s_cselect_b32 s24, s54, s62
	s_cselect_b32 s25, s53, s63
	s_add_i32 m0, s35, 0x0
	v_mfma_f32_16x16x32_bf16 v[98:101], v[200:203], v[216:219], v[98:101]
	global_load_lds_dwordx4 v102, s[22:23]
	s_add_i32 m0, s35, 0x2000
	v_mfma_f32_16x16x32_bf16 v[98:101], v[204:207], v[220:223], v[98:101]
	global_load_lds_dwordx4 v104, s[22:23]
	s_add_i32 m0, s35, 0x10000
	v_mfma_f32_16x16x32_bf16 v[94:97], v[208:211], v[216:219], v[94:97]
	global_load_lds_dwordx4 v102, s[24:25]
	s_add_i32 m0, s35, 0x12000
	v_mfma_f32_16x16x32_bf16 v[94:97], v[212:215], v[220:223], v[94:97]
	global_load_lds_dwordx4 v104, s[24:25]
	ds_read_b128 v[216:219], v188 offset:16384
	ds_read_b128 v[220:223], v188 offset:17408
	v_mfma_f32_16x16x32_bf16 v[90:93], v[200:203], v[224:227], v[90:93]
	v_mfma_f32_16x16x32_bf16 v[90:93], v[204:207], v[228:231], v[90:93]
	v_mfma_f32_16x16x32_bf16 v[86:89], v[208:211], v[224:227], v[86:89]
	v_mfma_f32_16x16x32_bf16 v[86:89], v[212:215], v[228:231], v[86:89]
	ds_read_b128 v[224:227], v188 offset:18432
	ds_read_b128 v[228:231], v188 offset:19456
	v_mfma_f32_16x16x32_bf16 v[82:85], v[200:203], v[232:235], v[82:85]
	global_load_dwordx4 v[6:9], v186, s[84:85]
	v_mfma_f32_16x16x32_bf16 v[82:85], v[204:207], v[236:239], v[82:85]
	s_add_u32 s86, s84, 0xcc000
	s_addc_u32 s87, s85, 0
	global_load_dwordx4 v[10:13], v186, s[86:87]
	v_mfma_f32_16x16x32_bf16 v[78:81], v[208:211], v[232:235], v[78:81]
	s_add_u32 s86, s84, 0x198000
	s_addc_u32 s87, s85, 0
	global_load_dwordx4 v[14:17], v186, s[86:87]
	v_mfma_f32_16x16x32_bf16 v[78:81], v[212:215], v[236:239], v[78:81]
	ds_read_b128 v[232:235], v188 offset:20480
	ds_read_b128 v[236:239], v188 offset:21504
	s_add_u32 s86, s84, 0x264000
	s_addc_u32 s87, s85, 0
	global_load_dwordx4 v[18:21], v186, s[86:87]
	v_mfma_f32_16x16x32_bf16 v[74:77], v[200:203], v[240:243], v[74:77]
	s_add_u32 s86, s84, 0x660000
	s_addc_u32 s87, s85, 0
	global_load_dwordx4 v[22:25], v186, s[86:87]
	v_mfma_f32_16x16x32_bf16 v[74:77], v[204:207], v[244:247], v[74:77]
	s_add_u32 s86, s84, 0x72c000
	s_addc_u32 s87, s85, 0
	global_load_dwordx4 v[26:29], v186, s[86:87]
	v_mfma_f32_16x16x32_bf16 v[70:73], v[208:211], v[240:243], v[70:73]
	s_add_u32 s86, s84, 0x7f8000
	s_addc_u32 s87, s85, 0
	global_load_dwordx4 v[30:33], v186, s[86:87]
	v_mfma_f32_16x16x32_bf16 v[70:73], v[212:215], v[244:247], v[70:73]
	ds_read_b128 v[240:243], v188 offset:22528
	ds_read_b128 v[244:247], v188 offset:23552
	s_add_u32 s84, s84, 0x8c4000
	s_addc_u32 s85, s85, 0
	global_load_dwordx4 v[34:37], v186, s[84:85]
	s_waitcnt vmcnt(14)
	s_waitcnt lgkmcnt(0)
	s_barrier
	s_add_u32 s26, s22, 0x100000
	s_addc_u32 s27, s23, 0
	s_add_i32 m0, s35, 0x4000
	v_mfma_f32_16x16x32_bf16 v[66:69], v[200:203], v[216:219], v[66:69]
	global_load_lds_dwordx4 v102, s[26:27]
	v_mfma_f32_16x16x32_bf16 v[58:61], v[200:203], v[224:227], v[58:61]
	ds_read_b128 v[106:109], v187 offset:33792
	s_add_i32 m0, s35, 0x6000
	v_mfma_f32_16x16x32_bf16 v[50:53], v[200:203], v[232:235], v[50:53]
	global_load_lds_dwordx4 v104, s[26:27]
	v_mfma_f32_16x16x32_bf16 v[42:45], v[200:203], v[240:243], v[42:45]
	ds_read_b128 v[160:163], v187 offset:34816
	ds_read_b128 v[200:203], v187 offset:32768
	v_mfma_f32_16x16x32_bf16 v[66:69], v[204:207], v[220:223], v[66:69]
	ds_read_b128 v[250:253], v187 offset:35840
	v_mfma_f32_16x16x32_bf16 v[62:65], v[208:211], v[216:219], v[62:65]
	v_mfma_f32_16x16x32_bf16 v[62:65], v[212:215], v[220:223], v[62:65]
	ds_read_b128 v[216:219], v188 offset:32768
	ds_read_b128 v[220:223], v188 offset:33792
	v_mfma_f32_16x16x32_bf16 v[58:61], v[204:207], v[228:231], v[58:61]
	v_mfma_f32_16x16x32_bf16 v[54:57], v[208:211], v[224:227], v[54:57]
	v_mfma_f32_16x16x32_bf16 v[54:57], v[212:215], v[228:231], v[54:57]
	ds_read_b128 v[224:227], v188 offset:34816
	ds_read_b128 v[228:231], v188 offset:35840
	v_mfma_f32_16x16x32_bf16 v[50:53], v[204:207], v[236:239], v[50:53]
	v_mfma_f32_16x16x32_bf16 v[46:49], v[208:211], v[232:235], v[46:49]
	v_mfma_f32_16x16x32_bf16 v[46:49], v[212:215], v[236:239], v[46:49]
	ds_read_b128 v[232:235], v188 offset:36864
	ds_read_b128 v[236:239], v188 offset:37888
	v_mfma_f32_16x16x32_bf16 v[42:45], v[204:207], v[244:247], v[42:45]
	v_mfma_f32_16x16x32_bf16 v[38:41], v[208:211], v[240:243], v[38:41]
	v_mfma_f32_16x16x32_bf16 v[38:41], v[212:215], v[244:247], v[38:41]
	ds_read_b128 v[240:243], v188 offset:38912
	ds_read_b128 v[244:247], v188 offset:39936
	s_waitcnt vmcnt(14)
	s_waitcnt lgkmcnt(0)
	s_barrier
	s_add_u32 s22, s22, 0x4000
	s_addc_u32 s23, s23, 0
	s_add_u32 s24, s24, 0x4000
	s_addc_u32 s25, s25, 0
	s_add_i32 m0, s35, 0x8000
	v_mfma_f32_16x16x32_bf16 v[98:101], v[200:203], v[216:219], v[98:101]
	global_load_lds_dwordx4 v102, s[22:23]
	s_add_i32 m0, s35, 0xa000
	v_mfma_f32_16x16x32_bf16 v[98:101], v[106:109], v[220:223], v[98:101]
	global_load_lds_dwordx4 v104, s[22:23]
	s_add_i32 m0, s35, 0x18000
	v_mfma_f32_16x16x32_bf16 v[94:97], v[160:163], v[216:219], v[94:97]
	global_load_lds_dwordx4 v102, s[24:25]
	s_add_i32 m0, s35, 0x1a000
	v_mfma_f32_16x16x32_bf16 v[94:97], v[250:253], v[220:223], v[94:97]
	global_load_lds_dwordx4 v104, s[24:25]
	ds_read_b128 v[216:219], v188 offset:49152
	ds_read_b128 v[220:223], v188 offset:50176
	v_mfma_f32_16x16x32_bf16 v[90:93], v[200:203], v[224:227], v[90:93]
	v_mfma_f32_16x16x32_bf16 v[90:93], v[106:109], v[228:231], v[90:93]
	v_mfma_f32_16x16x32_bf16 v[86:89], v[160:163], v[224:227], v[86:89]
	v_mfma_f32_16x16x32_bf16 v[86:89], v[250:253], v[228:231], v[86:89]
	ds_read_b128 v[224:227], v188 offset:51200
	ds_read_b128 v[228:231], v188 offset:52224
	v_mfma_f32_16x16x32_bf16 v[82:85], v[200:203], v[232:235], v[82:85]
	v_mfma_f32_16x16x32_bf16 v[82:85], v[106:109], v[236:239], v[82:85]
	v_mfma_f32_16x16x32_bf16 v[78:81], v[160:163], v[232:235], v[78:81]
	v_mfma_f32_16x16x32_bf16 v[78:81], v[250:253], v[236:239], v[78:81]
	ds_read_b128 v[232:235], v188 offset:53248
	ds_read_b128 v[236:239], v188 offset:54272
	v_mfma_f32_16x16x32_bf16 v[74:77], v[200:203], v[240:243], v[74:77]
	v_mfma_f32_16x16x32_bf16 v[74:77], v[106:109], v[244:247], v[74:77]
	v_mfma_f32_16x16x32_bf16 v[70:73], v[160:163], v[240:243], v[70:73]
	v_mfma_f32_16x16x32_bf16 v[70:73], v[250:253], v[244:247], v[70:73]
	ds_read_b128 v[240:243], v188 offset:55296
	ds_read_b128 v[244:247], v188 offset:56320
	s_waitcnt vmcnt(14)
	s_waitcnt lgkmcnt(0)
	s_barrier
	s_add_u32 s26, s22, 0x100000
	s_addc_u32 s27, s23, 0
	s_add_i32 m0, s35, 0xc000
	v_mfma_f32_16x16x32_bf16 v[66:69], v[200:203], v[216:219], v[66:69]
	global_load_lds_dwordx4 v102, s[26:27]
	v_mfma_f32_16x16x32_bf16 v[58:61], v[200:203], v[224:227], v[58:61]
	ds_read_b128 v[204:207], v187 offset:1024
	s_add_i32 m0, s35, 0xe000
	v_mfma_f32_16x16x32_bf16 v[50:53], v[200:203], v[232:235], v[50:53]
	global_load_lds_dwordx4 v104, s[26:27]
	v_mfma_f32_16x16x32_bf16 v[42:45], v[200:203], v[240:243], v[42:45]
	ds_read_b128 v[208:211], v187 offset:2048
	ds_read_b128 v[200:203], v187
	v_mfma_f32_16x16x32_bf16 v[66:69], v[106:109], v[220:223], v[66:69]
	ds_read_b128 v[212:215], v187 offset:3072
	v_mfma_f32_16x16x32_bf16 v[62:65], v[160:163], v[216:219], v[62:65]
	v_mfma_f32_16x16x32_bf16 v[62:65], v[250:253], v[220:223], v[62:65]
	ds_read_b128 v[216:219], v188
	ds_read_b128 v[220:223], v188 offset:1024
	v_mfma_f32_16x16x32_bf16 v[58:61], v[106:109], v[228:231], v[58:61]
	v_mfma_f32_16x16x32_bf16 v[54:57], v[160:163], v[224:227], v[54:57]
	v_mfma_f32_16x16x32_bf16 v[54:57], v[250:253], v[228:231], v[54:57]
	ds_read_b128 v[224:227], v188 offset:2048
	ds_read_b128 v[228:231], v188 offset:3072
	v_mfma_f32_16x16x32_bf16 v[50:53], v[106:109], v[236:239], v[50:53]
	v_mfma_f32_16x16x32_bf16 v[46:49], v[160:163], v[232:235], v[46:49]
	v_mfma_f32_16x16x32_bf16 v[46:49], v[250:253], v[236:239], v[46:49]
	ds_read_b128 v[232:235], v188 offset:4096
	ds_read_b128 v[236:239], v188 offset:5120
	v_mfma_f32_16x16x32_bf16 v[42:45], v[106:109], v[244:247], v[42:45]
	v_mfma_f32_16x16x32_bf16 v[38:41], v[160:163], v[240:243], v[38:41]
	v_mfma_f32_16x16x32_bf16 v[38:41], v[250:253], v[244:247], v[38:41]
	ds_read_b128 v[240:243], v188 offset:6144
	ds_read_b128 v[244:247], v188 offset:7168
	s_waitcnt vmcnt(6)
	s_waitcnt lgkmcnt(0)
	s_barrier
	s_branch .Lg16_tail_g0

.LBB0_965:
	v_and_b32_e32 v3, 48, v0
	v_lshrrev_b32_e32 v2, 4, v178
	v_lshl_or_b32 v3, v199, 6, v3
	v_lshlrev_b32_e32 v4, 3, v199
	s_lshl_b32 s2, s14, 12
	v_lshl_or_b32 v4, v2, 7, v4
	v_bitop3_b32 v5, s2, v3, v1 bitop3:0xf6
	s_lshl_b32 s2, s13, 11
	v_bitop3_b32 v200, s2, v3, v1 bitop3:0xf6
	v_or_b32_e32 v3, s12, v4
	s_lshl_b32 s2, s13, 5
	s_waitcnt vmcnt(4)
	v_or_b32_e32 v201, 0x2000, v3
	v_lshl_or_b32 v3, s14, 11, v4
	s_add_i32 s43, s12, 0
	v_lshl_or_b32 v2, v2, 3, s2
	v_mov_b32_e32 v50, 0
	s_mov_b32 s70, 0
	s_add_i32 s44, s43, 0xe000
	s_add_i32 s45, s43, 0x10000
	s_add_i32 s46, s43, 0x12000
	s_add_i32 s47, s43, 0x14000
	s_add_i32 s48, s43, 0x16000
	s_add_i32 s49, s43, 0x2000
	s_add_i32 s50, s43, 0x6000
	s_add_i32 s51, s43, 0x18000
	s_add_i32 s52, s43, 0x1a000
	s_add_i32 s53, s43, 0x1c000
	s_add_i32 s54, s43, 0x1e000
	s_add_i32 s55, s43, 0xa000
	v_lshl_or_b32 v202, s14, 6, v199
	s_add_i32 s56, s43, 0xd000
	s_add_i32 s57, s43, 0x11000
	s_add_i32 s58, s43, 0x15000
	s_add_i32 s59, s43, 0x1000
	s_add_i32 s60, s43, 0x5000
	s_add_i32 s61, s43, 0x19000
	s_add_i32 s62, s43, 0x1d000
	s_add_i32 s63, s43, 0x9000
	v_or_b32_e32 v203, 0x1400, v2
	v_mov_b64_e32 v[186:187], 0xa20
	v_mov_b64_e32 v[188:189], 0xa1f
	s_add_i32 s64, s43, 0xc000
	v_mov_b32_e32 v204, 0x7f7f7f7f
	s_add_i32 s65, s43, 0x4000
	s_add_i32 s66, s43, 0x8000
	s_mov_b32 s24, 0x3b800000
	s_mov_b32 s67, 0xcc00
	v_add_u32_e32 v205, 0, v5
	v_add_u32_e32 v206, 0, v3
	v_mov_b32_e32 v51, v50
	v_mov_b32_e32 v52, v50
	v_mov_b32_e32 v53, v50
	v_mov_b32_e32 v54, v50
	v_mov_b32_e32 v55, v50
	v_mov_b32_e32 v56, v50
	v_mov_b32_e32 v57, v50
	v_mov_b32_e32 v58, v50
	v_mov_b32_e32 v59, v50
	v_mov_b32_e32 v60, v50
	v_mov_b32_e32 v61, v50
	v_mov_b32_e32 v62, v50
	v_mov_b32_e32 v63, v50
	v_mov_b32_e32 v64, v50
	v_mov_b32_e32 v65, v50
	v_mov_b32_e32 v66, v50
	v_mov_b32_e32 v67, v50
	v_mov_b32_e32 v68, v50
	v_mov_b32_e32 v69, v50
	v_mov_b32_e32 v70, v50
	v_mov_b32_e32 v71, v50
	v_mov_b32_e32 v72, v50
	v_mov_b32_e32 v73, v50
	v_mov_b32_e32 v74, v50
	v_mov_b32_e32 v75, v50
	v_mov_b32_e32 v76, v50
	v_mov_b32_e32 v77, v50
	v_mov_b32_e32 v78, v50
	v_mov_b32_e32 v79, v50
	v_mov_b32_e32 v80, v50
	v_mov_b32_e32 v81, v50
	v_mov_b32_e32 v82, v50
	v_mov_b32_e32 v83, v50
	v_mov_b32_e32 v84, v50
	v_mov_b32_e32 v85, v50
	v_mov_b32_e32 v86, v50
	v_mov_b32_e32 v87, v50
	v_mov_b32_e32 v88, v50
	v_mov_b32_e32 v89, v50
	v_mov_b32_e32 v90, v50
	v_mov_b32_e32 v91, v50
	v_mov_b32_e32 v92, v50
	v_mov_b32_e32 v93, v50
	v_mov_b32_e32 v94, v50
	v_mov_b32_e32 v95, v50
	v_mov_b32_e32 v96, v50
	v_mov_b32_e32 v97, v50
	v_mov_b32_e32 v98, v50
	v_mov_b32_e32 v99, v50
	v_mov_b32_e32 v100, v50
	v_mov_b32_e32 v101, v50
	v_mov_b32_e32 v102, v50
	v_mov_b32_e32 v103, v50
	v_mov_b32_e32 v104, v50
	v_mov_b32_e32 v105, v50
	v_mov_b32_e32 v106, v50
	v_mov_b32_e32 v107, v50
	v_mov_b32_e32 v108, v50
	v_mov_b32_e32 v109, v50
	v_mov_b32_e32 v110, v50
	v_mov_b32_e32 v111, v50
	v_mov_b32_e32 v112, v50
	v_mov_b32_e32 v113, v50
	v_mov_b32_e32 v114, v50
	v_mov_b32_e32 v115, v50
	v_mov_b32_e32 v116, v50
	v_mov_b32_e32 v117, v50
	v_mov_b32_e32 v118, v50
	v_mov_b32_e32 v119, v50
	v_mov_b32_e32 v120, v50
	v_mov_b32_e32 v121, v50
	v_mov_b32_e32 v122, v50
	v_mov_b32_e32 v123, v50
	v_mov_b32_e32 v124, v50
	v_mov_b32_e32 v125, v50
	v_mov_b32_e32 v126, v50
	v_mov_b32_e32 v127, v50
	v_mov_b32_e32 v128, v50
	v_mov_b32_e32 v129, v50
	v_mov_b32_e32 v130, v50
	v_mov_b32_e32 v131, v50
	v_mov_b32_e32 v132, v50
	v_mov_b32_e32 v133, v50
	v_mov_b32_e32 v134, v50
	v_mov_b32_e32 v135, v50
	v_mov_b32_e32 v136, v50
	v_mov_b32_e32 v137, v50
	v_mov_b32_e32 v138, v50
	v_mov_b32_e32 v139, v50
	v_mov_b32_e32 v140, v50
	v_mov_b32_e32 v141, v50
	v_mov_b32_e32 v142, v50
	v_mov_b32_e32 v143, v50
	v_mov_b32_e32 v144, v50
	v_mov_b32_e32 v145, v50
	v_mov_b32_e32 v146, v50
	v_mov_b32_e32 v147, v50
	v_mov_b32_e32 v148, v50
	v_mov_b32_e32 v149, v50
	v_mov_b32_e32 v150, v50
	v_mov_b32_e32 v151, v50
	v_mov_b32_e32 v152, v50
	v_mov_b32_e32 v153, v50
	v_mov_b32_e32 v154, v50
	v_mov_b32_e32 v155, v50
	v_mov_b32_e32 v156, v50
	v_mov_b32_e32 v157, v50
	v_mov_b32_e32 v158, v50
	v_mov_b32_e32 v159, v50
	v_mov_b32_e32 v160, v50
	v_mov_b32_e32 v161, v50
	v_mov_b32_e32 v162, v50
	v_mov_b32_e32 v163, v50
	v_mov_b32_e32 v164, v50
	v_mov_b32_e32 v165, v50
	v_mov_b32_e32 v166, v50
	v_mov_b32_e32 v167, v50
	v_mov_b32_e32 v168, v50
	v_mov_b32_e32 v169, v50
	v_mov_b32_e32 v170, v50
	v_mov_b32_e32 v171, v50
	v_mov_b32_e32 v172, v50
	v_mov_b32_e32 v173, v50
	v_mov_b32_e32 v174, v50
	v_mov_b32_e32 v175, v50
	v_mov_b32_e32 v176, v50
	v_mov_b32_e32 v177, v50
	s_barrier
	s_mov_b32 s32, 1
	s_mov_b32 s84, 0
	v_mov_b32_e32 v244, v180
	v_mov_b32_e32 v245, v182
	v_mov_b32_e32 v246, v184
	s_branch .LBB0_968

.Lsp0_top_L1:
	s_cmp_eq_i32 s73, -2
	s_cselect_b32 s85, s84, 0
	s_add_u32 s34, s2, 0xfffa3000
	s_addc_u32 s35, s3, -1
	s_cmp_eq_u32 s73, 28
	s_cselect_b32 s28, s26, s33
	s_cselect_b32 s29, s27, s72
	s_cselect_b32 s30, s14, s34
	s_cselect_b32 s31, s15, s35
	s_add_u32 s34, s28, 0x60000
	s_addc_u32 s35, s29, 0
	s_mov_b32 m0, s49
	v_mfma_scale_f32_16x16x128_f8f6f4 v[174:177], v[20:25], v[44:49], v[174:177], v204, v204 op_sel_hi:[0,0,0] cbsz:2 blgp:2
	global_load_lds_dwordx4 v246, s[30:31]
	v_mfma_scale_f32_16x16x128_f8f6f4 v[170:173], v[14:19], v[44:49], v[170:173], v204, v204 op_sel_hi:[0,0,0] cbsz:2 blgp:2
	ds_read_b128 v[208:211], v205 offset:16384
	v_mfma_scale_f32_16x16x128_f8f6f4 v[166:169], v[20:25], v[38:43], v[166:169], v204, v204 op_sel_hi:[0,0,0] cbsz:2 blgp:2
	ds_read_b64 v[212:213], v206 offset:24576
	s_mov_b32 m0, s46
	v_mfma_scale_f32_16x16x128_f8f6f4 v[162:165], v[14:19], v[38:43], v[162:165], v204, v204 op_sel_hi:[0,0,0] cbsz:2 blgp:2
	global_load_lds_dwordx4 v246, s[28:29]
	v_mfma_scale_f32_16x16x128_f8f6f4 v[158:161], v[20:25], v[32:37], v[158:161], v204, v204 op_sel_hi:[0,0,0] cbsz:2 blgp:2
	ds_read_b128 v[214:217], v205 offset:17408
	v_mfma_scale_f32_16x16x128_f8f6f4 v[154:157], v[14:19], v[32:37], v[154:157], v204, v204 op_sel_hi:[0,0,0] cbsz:2 blgp:2
	ds_read_b64 v[218:219], v206 offset:25088
	s_mov_b32 m0, s47
	v_mfma_scale_f32_16x16x128_f8f6f4 v[150:153], v[20:25], v[26:31], v[150:153], v204, v204 op_sel_hi:[0,0,0] cbsz:2 blgp:2
	global_load_lds_dwordx4 v244, s[34:35]
	v_mfma_scale_f32_16x16x128_f8f6f4 v[146:149], v[14:19], v[26:31], v[146:149], v204, v204 op_sel_hi:[0,0,0] cbsz:2 blgp:2
	ds_read_b128 v[220:223], v205 offset:18432
	v_mfma_scale_f32_16x16x128_f8f6f4 v[142:145], v[8:13], v[44:49], v[142:145], v204, v204 op_sel_hi:[0,0,0] cbsz:2 blgp:2
	ds_read_b64 v[224:225], v206 offset:25600
	s_mov_b32 m0, s58
	v_mfma_scale_f32_16x16x128_f8f6f4 v[138:141], v[2:7], v[44:49], v[138:141], v204, v204 op_sel_hi:[0,0,0] cbsz:2 blgp:2
	global_load_lds_dwordx4 v245, s[34:35]
	v_mfma_scale_f32_16x16x128_f8f6f4 v[134:137], v[8:13], v[38:43], v[134:137], v204, v204 op_sel_hi:[0,0,0] cbsz:2 blgp:2
	ds_read_b128 v[226:229], v205 offset:19456
	v_mfma_scale_f32_16x16x128_f8f6f4 v[130:133], v[2:7], v[38:43], v[130:133], v204, v204 op_sel_hi:[0,0,0] cbsz:2 blgp:2
	ds_read_b64 v[230:231], v206 offset:26112
	v_mfma_scale_f32_16x16x128_f8f6f4 v[126:129], v[8:13], v[32:37], v[126:129], v204, v204 op_sel_hi:[0,0,0] cbsz:2 blgp:2
	v_mfma_scale_f32_16x16x128_f8f6f4 v[122:125], v[2:7], v[32:37], v[122:125], v204, v204 op_sel_hi:[0,0,0] cbsz:2 blgp:2
	v_mfma_scale_f32_16x16x128_f8f6f4 v[118:121], v[8:13], v[26:31], v[118:121], v204, v204 op_sel_hi:[0,0,0] cbsz:2 blgp:2
	v_mfma_scale_f32_16x16x128_f8f6f4 v[114:117], v[2:7], v[26:31], v[114:117], v204, v204 op_sel_hi:[0,0,0] cbsz:2 blgp:2
	s_cmp_eq_u32 s85, 1
	s_cbranch_scc1 .Lsp0_fw1_L1
	s_waitcnt vmcnt(6)
	s_branch .Lsp0_fj1_L1

.Lsp0_fj1_L1:
	s_waitcnt lgkmcnt(0)
	s_barrier
	s_add_u32 s34, s30, 0x60000
	s_addc_u32 s35, s31, 0
	s_mov_b32 m0, s65
	v_mfma_scale_f32_16x16x128_f8f6f4 v[110:113], v[20:25], v[208:213], v[110:113], v204, v204 op_sel_hi:[0,0,0] cbsz:2 blgp:2
	global_load_lds_dwordx4 v244, s[34:35]
	ds_read_b128 v[44:47], v205 offset:32768
	s_mov_b32 m0, s60
	v_mfma_scale_f32_16x16x128_f8f6f4 v[106:109], v[14:19], v[208:213], v[106:109], v204, v204 op_sel_hi:[0,0,0] cbsz:2 blgp:2
	ds_read_b64 v[48:49], v206 offset:40960
	global_load_lds_dwordx4 v245, s[34:35]
	v_mfma_scale_f32_16x16x128_f8f6f4 v[102:105], v[20:25], v[214:219], v[102:105], v204, v204 op_sel_hi:[0,0,0] cbsz:2 blgp:2
	ds_read_b128 v[38:41], v205 offset:33792
	ds_read_b64 v[42:43], v206 offset:41472
	v_mfma_scale_f32_16x16x128_f8f6f4 v[98:101], v[14:19], v[214:219], v[98:101], v204, v204 op_sel_hi:[0,0,0] cbsz:2 blgp:2
	ds_read_b128 v[32:35], v205 offset:34816
	ds_read_b64 v[36:37], v206 offset:41984
	v_mfma_scale_f32_16x16x128_f8f6f4 v[94:97], v[20:25], v[220:225], v[94:97], v204, v204 op_sel_hi:[0,0,0] cbsz:2 blgp:2
	ds_read_b128 v[26:29], v205 offset:35840
	ds_read_b64 v[30:31], v206 offset:42496
	v_mfma_scale_f32_16x16x128_f8f6f4 v[90:93], v[14:19], v[220:225], v[90:93], v204, v204 op_sel_hi:[0,0,0] cbsz:2 blgp:2
	ds_read_b128 v[232:235], v247 offset:32768
	ds_read_b64 v[236:237], v248 offset:32768
	v_mfma_scale_f32_16x16x128_f8f6f4 v[86:89], v[20:25], v[226:231], v[86:89], v204, v204 op_sel_hi:[0,0,0] cbsz:2 blgp:2
	ds_read_b128 v[238:241], v247 offset:33792
	ds_read_b64 v[242:243], v248 offset:33280
	v_mfma_scale_f32_16x16x128_f8f6f4 v[82:85], v[14:19], v[226:231], v[82:85], v204, v204 op_sel_hi:[0,0,0] cbsz:2 blgp:2
	ds_read_b128 v[180:183], v247 offset:49152
	ds_read_b64 v[184:185], v248 offset:49152
	v_mfma_scale_f32_16x16x128_f8f6f4 v[78:81], v[8:13], v[208:213], v[78:81], v204, v204 op_sel_hi:[0,0,0] cbsz:2 blgp:2
	ds_read_b128 v[250:253], v247 offset:50176
	ds_read_b64 v[254:255], v248 offset:49664
	v_mfma_scale_f32_16x16x128_f8f6f4 v[74:77], v[2:7], v[208:213], v[74:77], v204, v204 op_sel_hi:[0,0,0] cbsz:2 blgp:2
	v_mfma_scale_f32_16x16x128_f8f6f4 v[70:73], v[8:13], v[214:219], v[70:73], v204, v204 op_sel_hi:[0,0,0] cbsz:2 blgp:2
	v_mfma_scale_f32_16x16x128_f8f6f4 v[66:69], v[2:7], v[214:219], v[66:69], v204, v204 op_sel_hi:[0,0,0] cbsz:2 blgp:2
	v_mfma_scale_f32_16x16x128_f8f6f4 v[62:65], v[8:13], v[220:225], v[62:65], v204, v204 op_sel_hi:[0,0,0] cbsz:2 blgp:2
	v_mfma_scale_f32_16x16x128_f8f6f4 v[58:61], v[2:7], v[220:225], v[58:61], v204, v204 op_sel_hi:[0,0,0] cbsz:2 blgp:2
	v_mfma_scale_f32_16x16x128_f8f6f4 v[54:57], v[8:13], v[226:231], v[54:57], v204, v204 op_sel_hi:[0,0,0] cbsz:2 blgp:2
	v_mfma_scale_f32_16x16x128_f8f6f4 v[50:53], v[2:7], v[226:231], v[50:53], v204, v204 op_sel_hi:[0,0,0] cbsz:2 blgp:2
	s_cmp_eq_u32 s85, 1
	s_cbranch_scc1 .Lsp0_fw2_L1
	s_waitcnt vmcnt(6)
	s_branch .Lsp0_fj2_L1

.Lsp0_fj2_L1:
	s_waitcnt lgkmcnt(0)
	s_barrier
	s_add_u32 s30, s30, 0x3000
	s_addc_u32 s31, s31, 0
	s_add_u32 s28, s28, 0x3000
	s_addc_u32 s29, s29, 0
	s_add_u32 s34, s28, 0x60000
	s_addc_u32 s35, s29, 0
	s_mov_b32 m0, s55
	v_mfma_scale_f32_16x16x128_f8f6f4 v[174:177], v[232:237], v[44:49], v[174:177], v204, v204 op_sel_hi:[0,0,0] cbsz:2 blgp:2
	global_load_lds_dwordx4 v246, s[30:31]
	v_mfma_scale_f32_16x16x128_f8f6f4 v[170:173], v[238:243], v[44:49], v[170:173], v204, v204 op_sel_hi:[0,0,0] cbsz:2 blgp:2
	ds_read_b128 v[208:211], v205 offset:49152
	v_mfma_scale_f32_16x16x128_f8f6f4 v[166:169], v[232:237], v[38:43], v[166:169], v204, v204 op_sel_hi:[0,0,0] cbsz:2 blgp:2
	ds_read_b64 v[212:213], v206 offset:57344
	s_mov_b32 m0, s52
	v_mfma_scale_f32_16x16x128_f8f6f4 v[162:165], v[238:243], v[38:43], v[162:165], v204, v204 op_sel_hi:[0,0,0] cbsz:2 blgp:2
	global_load_lds_dwordx4 v246, s[28:29]
	v_mfma_scale_f32_16x16x128_f8f6f4 v[158:161], v[232:237], v[32:37], v[158:161], v204, v204 op_sel_hi:[0,0,0] cbsz:2 blgp:2
	ds_read_b128 v[214:217], v205 offset:50176
	v_mfma_scale_f32_16x16x128_f8f6f4 v[154:157], v[238:243], v[32:37], v[154:157], v204, v204 op_sel_hi:[0,0,0] cbsz:2 blgp:2
	ds_read_b64 v[218:219], v206 offset:57856
	s_mov_b32 m0, s53
	v_mfma_scale_f32_16x16x128_f8f6f4 v[150:153], v[232:237], v[26:31], v[150:153], v204, v204 op_sel_hi:[0,0,0] cbsz:2 blgp:2
	global_load_lds_dwordx4 v244, s[34:35]
	v_mfma_scale_f32_16x16x128_f8f6f4 v[146:149], v[238:243], v[26:31], v[146:149], v204, v204 op_sel_hi:[0,0,0] cbsz:2 blgp:2
	ds_read_b128 v[220:223], v205 offset:51200
	v_mfma_scale_f32_16x16x128_f8f6f4 v[142:145], v[180:185], v[44:49], v[142:145], v204, v204 op_sel_hi:[0,0,0] cbsz:2 blgp:2
	ds_read_b64 v[224:225], v206 offset:58368
	s_mov_b32 m0, s62
	v_mfma_scale_f32_16x16x128_f8f6f4 v[138:141], v[250:255], v[44:49], v[138:141], v204, v204 op_sel_hi:[0,0,0] cbsz:2 blgp:2
	global_load_lds_dwordx4 v245, s[34:35]
	v_mfma_scale_f32_16x16x128_f8f6f4 v[134:137], v[180:185], v[38:43], v[134:137], v204, v204 op_sel_hi:[0,0,0] cbsz:2 blgp:2
	ds_read_b128 v[226:229], v205 offset:52224
	v_mfma_scale_f32_16x16x128_f8f6f4 v[130:133], v[250:255], v[38:43], v[130:133], v204, v204 op_sel_hi:[0,0,0] cbsz:2 blgp:2
	ds_read_b64 v[230:231], v206 offset:58880
	v_mfma_scale_f32_16x16x128_f8f6f4 v[126:129], v[180:185], v[32:37], v[126:129], v204, v204 op_sel_hi:[0,0,0] cbsz:2 blgp:2
	v_mfma_scale_f32_16x16x128_f8f6f4 v[122:125], v[250:255], v[32:37], v[122:125], v204, v204 op_sel_hi:[0,0,0] cbsz:2 blgp:2
	v_mfma_scale_f32_16x16x128_f8f6f4 v[118:121], v[180:185], v[26:31], v[118:121], v204, v204 op_sel_hi:[0,0,0] cbsz:2 blgp:2
	v_mfma_scale_f32_16x16x128_f8f6f4 v[114:117], v[250:255], v[26:31], v[114:117], v204, v204 op_sel_hi:[0,0,0] cbsz:2 blgp:2
	s_waitcnt vmcnt(6)
	s_waitcnt lgkmcnt(0)
	s_barrier
	s_add_u32 s34, s30, 0x60000
	s_addc_u32 s35, s31, 0
	s_mov_b32 m0, s64
	v_mfma_scale_f32_16x16x128_f8f6f4 v[110:113], v[232:237], v[208:213], v[110:113], v204, v204 op_sel_hi:[0,0,0] cbsz:2 blgp:2
	global_load_lds_dwordx4 v244, s[34:35]
	ds_read_b128 v[44:47], v205
	s_mov_b32 m0, s56
	v_mfma_scale_f32_16x16x128_f8f6f4 v[106:109], v[238:243], v[208:213], v[106:109], v204, v204 op_sel_hi:[0,0,0] cbsz:2 blgp:2
	ds_read_b64 v[48:49], v206 offset:8192
	global_load_lds_dwordx4 v245, s[34:35]
	v_mfma_scale_f32_16x16x128_f8f6f4 v[102:105], v[232:237], v[214:219], v[102:105], v204, v204 op_sel_hi:[0,0,0] cbsz:2 blgp:2
	ds_read_b128 v[38:41], v205 offset:1024
	ds_read_b64 v[42:43], v206 offset:8704
	v_mfma_scale_f32_16x16x128_f8f6f4 v[98:101], v[238:243], v[214:219], v[98:101], v204, v204 op_sel_hi:[0,0,0] cbsz:2 blgp:2
	ds_read_b128 v[32:35], v205 offset:2048
	ds_read_b64 v[36:37], v206 offset:9216
	v_mfma_scale_f32_16x16x128_f8f6f4 v[94:97], v[232:237], v[220:225], v[94:97], v204, v204 op_sel_hi:[0,0,0] cbsz:2 blgp:2
	ds_read_b128 v[26:29], v205 offset:3072
	ds_read_b64 v[30:31], v206 offset:9728
	v_mfma_scale_f32_16x16x128_f8f6f4 v[90:93], v[238:243], v[220:225], v[90:93], v204, v204 op_sel_hi:[0,0,0] cbsz:2 blgp:2
	ds_read_b128 v[20:23], v247
	ds_read_b64 v[24:25], v248
	v_mfma_scale_f32_16x16x128_f8f6f4 v[86:89], v[232:237], v[226:231], v[86:89], v204, v204 op_sel_hi:[0,0,0] cbsz:2 blgp:2
	ds_read_b128 v[14:17], v247 offset:1024
	ds_read_b64 v[18:19], v248 offset:512
	v_mfma_scale_f32_16x16x128_f8f6f4 v[82:85], v[238:243], v[226:231], v[82:85], v204, v204 op_sel_hi:[0,0,0] cbsz:2 blgp:2
	ds_read_b128 v[8:11], v247 offset:16384
	ds_read_b64 v[12:13], v248 offset:16384
	v_mfma_scale_f32_16x16x128_f8f6f4 v[78:81], v[180:185], v[208:213], v[78:81], v204, v204 op_sel_hi:[0,0,0] cbsz:2 blgp:2
	ds_read_b128 v[2:5], v247 offset:17408
	ds_read_b64 v[6:7], v248 offset:16896
	v_mfma_scale_f32_16x16x128_f8f6f4 v[74:77], v[250:255], v[208:213], v[74:77], v204, v204 op_sel_hi:[0,0,0] cbsz:2 blgp:2
	v_mfma_scale_f32_16x16x128_f8f6f4 v[70:73], v[180:185], v[214:219], v[70:73], v204, v204 op_sel_hi:[0,0,0] cbsz:2 blgp:2
	v_mfma_scale_f32_16x16x128_f8f6f4 v[66:69], v[250:255], v[214:219], v[66:69], v204, v204 op_sel_hi:[0,0,0] cbsz:2 blgp:2
	v_mfma_scale_f32_16x16x128_f8f6f4 v[62:65], v[180:185], v[220:225], v[62:65], v204, v204 op_sel_hi:[0,0,0] cbsz:2 blgp:2
	v_mfma_scale_f32_16x16x128_f8f6f4 v[58:61], v[250:255], v[220:225], v[58:61], v204, v204 op_sel_hi:[0,0,0] cbsz:2 blgp:2
	v_mfma_scale_f32_16x16x128_f8f6f4 v[54:57], v[180:185], v[226:231], v[54:57], v204, v204 op_sel_hi:[0,0,0] cbsz:2 blgp:2
	v_mfma_scale_f32_16x16x128_f8f6f4 v[50:53], v[250:255], v[226:231], v[50:53], v204, v204 op_sel_hi:[0,0,0] cbsz:2 blgp:2
	s_waitcnt vmcnt(6)
	s_waitcnt lgkmcnt(0)
	s_barrier
	s_add_i32 s73, s73, 2
	s_add_u32 s2, s2, 0x6000
	s_addc_u32 s3, s3, 0
	s_add_u32 s33, s33, 0x6000
	s_addc_u32 s72, s72, 0
	s_cmp_gt_u32 s73, 29
	s_cbranch_scc0 .Lsp0_top_L1
	s_mov_b32 s84, 1
	s_branch .LBB0_992

.Lsp1_top_L1:
	s_cmp_eq_i32 s73, -2
	s_cselect_b32 s85, s84, 0
	s_add_u32 s34, s2, 0xfffa3000
	s_addc_u32 s35, s3, -1
	s_cmp_eq_u32 s73, 28
	s_cselect_b32 s28, s26, s33
	s_cselect_b32 s29, s27, s72
	s_cselect_b32 s30, s14, s34
	s_cselect_b32 s31, s15, s35
	s_add_u32 s34, s28, 0x60000
	s_addc_u32 s35, s29, 0
	s_mov_b32 m0, s43
	v_mfma_scale_f32_16x16x128_f8f6f4 v[174:177], v[20:25], v[44:49], v[174:177], v204, v204 op_sel_hi:[0,0,0] cbsz:2 blgp:2
	global_load_lds_dwordx4 v244, s[30:31]
	v_mfma_scale_f32_16x16x128_f8f6f4 v[170:173], v[14:19], v[44:49], v[170:173], v204, v204 op_sel_hi:[0,0,0] cbsz:2 blgp:2
	ds_read_b128 v[208:211], v205 offset:16384
	v_mfma_scale_f32_16x16x128_f8f6f4 v[166:169], v[20:25], v[38:43], v[166:169], v204, v204 op_sel_hi:[0,0,0] cbsz:2 blgp:2
	ds_read_b64 v[212:213], v206 offset:24576
	s_mov_b32 m0, s59
	v_mfma_scale_f32_16x16x128_f8f6f4 v[162:165], v[14:19], v[38:43], v[162:165], v204, v204 op_sel_hi:[0,0,0] cbsz:2 blgp:2
	global_load_lds_dwordx4 v245, s[30:31]
	v_mfma_scale_f32_16x16x128_f8f6f4 v[158:161], v[20:25], v[32:37], v[158:161], v204, v204 op_sel_hi:[0,0,0] cbsz:2 blgp:2
	ds_read_b128 v[214:217], v205 offset:17408
	v_mfma_scale_f32_16x16x128_f8f6f4 v[154:157], v[14:19], v[32:37], v[154:157], v204, v204 op_sel_hi:[0,0,0] cbsz:2 blgp:2
	ds_read_b64 v[218:219], v206 offset:25088
	s_mov_b32 m0, s45
	v_mfma_scale_f32_16x16x128_f8f6f4 v[150:153], v[20:25], v[26:31], v[150:153], v204, v204 op_sel_hi:[0,0,0] cbsz:2 blgp:2
	global_load_lds_dwordx4 v244, s[28:29]
	v_mfma_scale_f32_16x16x128_f8f6f4 v[146:149], v[14:19], v[26:31], v[146:149], v204, v204 op_sel_hi:[0,0,0] cbsz:2 blgp:2
	ds_read_b128 v[220:223], v205 offset:18432
	v_mfma_scale_f32_16x16x128_f8f6f4 v[142:145], v[8:13], v[44:49], v[142:145], v204, v204 op_sel_hi:[0,0,0] cbsz:2 blgp:2
	ds_read_b64 v[224:225], v206 offset:25600
	s_mov_b32 m0, s57
	v_mfma_scale_f32_16x16x128_f8f6f4 v[138:141], v[2:7], v[44:49], v[138:141], v204, v204 op_sel_hi:[0,0,0] cbsz:2 blgp:2
	global_load_lds_dwordx4 v245, s[28:29]
	v_mfma_scale_f32_16x16x128_f8f6f4 v[134:137], v[8:13], v[38:43], v[134:137], v204, v204 op_sel_hi:[0,0,0] cbsz:2 blgp:2
	ds_read_b128 v[226:229], v205 offset:19456
	v_mfma_scale_f32_16x16x128_f8f6f4 v[130:133], v[2:7], v[38:43], v[130:133], v204, v204 op_sel_hi:[0,0,0] cbsz:2 blgp:2
	ds_read_b64 v[230:231], v206 offset:26112
	s_mov_b32 m0, s48
	v_mfma_scale_f32_16x16x128_f8f6f4 v[126:129], v[8:13], v[32:37], v[126:129], v204, v204 op_sel_hi:[0,0,0] cbsz:2 blgp:2
	global_load_lds_dwordx4 v246, s[34:35]
	v_mfma_scale_f32_16x16x128_f8f6f4 v[122:125], v[2:7], v[32:37], v[122:125], v204, v204 op_sel_hi:[0,0,0] cbsz:2 blgp:2
	v_mfma_scale_f32_16x16x128_f8f6f4 v[118:121], v[8:13], v[26:31], v[118:121], v204, v204 op_sel_hi:[0,0,0] cbsz:2 blgp:2
	v_mfma_scale_f32_16x16x128_f8f6f4 v[114:117], v[2:7], v[26:31], v[114:117], v204, v204 op_sel_hi:[0,0,0] cbsz:2 blgp:2
	s_cmp_eq_u32 s85, 1
	s_cbranch_scc1 .Lsp1_fw1_L1
	s_waitcnt vmcnt(6)
	s_branch .Lsp1_fj1_L1

.Lsp1_fj1_L1:
	s_waitcnt lgkmcnt(0)
	s_barrier
	s_add_u32 s34, s30, 0x60000
	s_addc_u32 s35, s31, 0
	s_mov_b32 m0, s50
	v_mfma_scale_f32_16x16x128_f8f6f4 v[110:113], v[20:25], v[208:213], v[110:113], v204, v204 op_sel_hi:[0,0,0] cbsz:2 blgp:2
	global_load_lds_dwordx4 v246, s[34:35]
	ds_read_b128 v[44:47], v205 offset:32768
	v_mfma_scale_f32_16x16x128_f8f6f4 v[106:109], v[14:19], v[208:213], v[106:109], v204, v204 op_sel_hi:[0,0,0] cbsz:2 blgp:2
	ds_read_b64 v[48:49], v206 offset:40960
	ds_read_b128 v[38:41], v205 offset:33792
	v_mfma_scale_f32_16x16x128_f8f6f4 v[102:105], v[20:25], v[214:219], v[102:105], v204, v204 op_sel_hi:[0,0,0] cbsz:2 blgp:2
	ds_read_b64 v[42:43], v206 offset:41472
	ds_read_b128 v[32:35], v205 offset:34816
	v_mfma_scale_f32_16x16x128_f8f6f4 v[98:101], v[14:19], v[214:219], v[98:101], v204, v204 op_sel_hi:[0,0,0] cbsz:2 blgp:2
	ds_read_b64 v[36:37], v206 offset:41984
	ds_read_b128 v[26:29], v205 offset:35840
	v_mfma_scale_f32_16x16x128_f8f6f4 v[94:97], v[20:25], v[220:225], v[94:97], v204, v204 op_sel_hi:[0,0,0] cbsz:2 blgp:2
	ds_read_b64 v[30:31], v206 offset:42496
	ds_read_b128 v[232:235], v247 offset:32768
	v_mfma_scale_f32_16x16x128_f8f6f4 v[90:93], v[14:19], v[220:225], v[90:93], v204, v204 op_sel_hi:[0,0,0] cbsz:2 blgp:2
	ds_read_b64 v[236:237], v248 offset:32768
	ds_read_b128 v[238:241], v247 offset:33792
	v_mfma_scale_f32_16x16x128_f8f6f4 v[86:89], v[20:25], v[226:231], v[86:89], v204, v204 op_sel_hi:[0,0,0] cbsz:2 blgp:2
	ds_read_b64 v[242:243], v248 offset:33280
	ds_read_b128 v[180:183], v247 offset:49152
	v_mfma_scale_f32_16x16x128_f8f6f4 v[82:85], v[14:19], v[226:231], v[82:85], v204, v204 op_sel_hi:[0,0,0] cbsz:2 blgp:2
	ds_read_b64 v[184:185], v248 offset:49152
	ds_read_b128 v[250:253], v247 offset:50176
	v_mfma_scale_f32_16x16x128_f8f6f4 v[78:81], v[8:13], v[208:213], v[78:81], v204, v204 op_sel_hi:[0,0,0] cbsz:2 blgp:2
	ds_read_b64 v[254:255], v248 offset:49664
	v_mfma_scale_f32_16x16x128_f8f6f4 v[74:77], v[2:7], v[208:213], v[74:77], v204, v204 op_sel_hi:[0,0,0] cbsz:2 blgp:2
	v_mfma_scale_f32_16x16x128_f8f6f4 v[70:73], v[8:13], v[214:219], v[70:73], v204, v204 op_sel_hi:[0,0,0] cbsz:2 blgp:2
	v_mfma_scale_f32_16x16x128_f8f6f4 v[66:69], v[2:7], v[214:219], v[66:69], v204, v204 op_sel_hi:[0,0,0] cbsz:2 blgp:2
	v_mfma_scale_f32_16x16x128_f8f6f4 v[62:65], v[8:13], v[220:225], v[62:65], v204, v204 op_sel_hi:[0,0,0] cbsz:2 blgp:2
	v_mfma_scale_f32_16x16x128_f8f6f4 v[58:61], v[2:7], v[220:225], v[58:61], v204, v204 op_sel_hi:[0,0,0] cbsz:2 blgp:2
	v_mfma_scale_f32_16x16x128_f8f6f4 v[54:57], v[8:13], v[226:231], v[54:57], v204, v204 op_sel_hi:[0,0,0] cbsz:2 blgp:2
	v_mfma_scale_f32_16x16x128_f8f6f4 v[50:53], v[2:7], v[226:231], v[50:53], v204, v204 op_sel_hi:[0,0,0] cbsz:2 blgp:2
	s_cmp_eq_u32 s85, 1
	s_cbranch_scc1 .Lsp1_fw2_L1
	s_waitcnt vmcnt(6)
	s_branch .Lsp1_fj2_L1

.Lsp1_fj2_L1:
	s_waitcnt lgkmcnt(0)
	s_barrier
	s_add_u32 s30, s30, 0x3000
	s_addc_u32 s31, s31, 0
	s_add_u32 s28, s28, 0x3000
	s_addc_u32 s29, s29, 0
	s_add_u32 s34, s28, 0x60000
	s_addc_u32 s35, s29, 0
	s_mov_b32 m0, s66
	v_mfma_scale_f32_16x16x128_f8f6f4 v[174:177], v[232:237], v[44:49], v[174:177], v204, v204 op_sel_hi:[0,0,0] cbsz:2 blgp:2
	global_load_lds_dwordx4 v244, s[30:31]
	v_mfma_scale_f32_16x16x128_f8f6f4 v[170:173], v[238:243], v[44:49], v[170:173], v204, v204 op_sel_hi:[0,0,0] cbsz:2 blgp:2
	ds_read_b128 v[208:211], v205 offset:49152
	v_mfma_scale_f32_16x16x128_f8f6f4 v[166:169], v[232:237], v[38:43], v[166:169], v204, v204 op_sel_hi:[0,0,0] cbsz:2 blgp:2
	ds_read_b64 v[212:213], v206 offset:57344
	s_mov_b32 m0, s63
	v_mfma_scale_f32_16x16x128_f8f6f4 v[162:165], v[238:243], v[38:43], v[162:165], v204, v204 op_sel_hi:[0,0,0] cbsz:2 blgp:2
	global_load_lds_dwordx4 v245, s[30:31]
	v_mfma_scale_f32_16x16x128_f8f6f4 v[158:161], v[232:237], v[32:37], v[158:161], v204, v204 op_sel_hi:[0,0,0] cbsz:2 blgp:2
	ds_read_b128 v[214:217], v205 offset:50176
	v_mfma_scale_f32_16x16x128_f8f6f4 v[154:157], v[238:243], v[32:37], v[154:157], v204, v204 op_sel_hi:[0,0,0] cbsz:2 blgp:2
	ds_read_b64 v[218:219], v206 offset:57856
	s_mov_b32 m0, s51
	v_mfma_scale_f32_16x16x128_f8f6f4 v[150:153], v[232:237], v[26:31], v[150:153], v204, v204 op_sel_hi:[0,0,0] cbsz:2 blgp:2
	global_load_lds_dwordx4 v244, s[28:29]
	v_mfma_scale_f32_16x16x128_f8f6f4 v[146:149], v[238:243], v[26:31], v[146:149], v204, v204 op_sel_hi:[0,0,0] cbsz:2 blgp:2
	ds_read_b128 v[220:223], v205 offset:51200
	v_mfma_scale_f32_16x16x128_f8f6f4 v[142:145], v[180:185], v[44:49], v[142:145], v204, v204 op_sel_hi:[0,0,0] cbsz:2 blgp:2
	ds_read_b64 v[224:225], v206 offset:58368
	s_mov_b32 m0, s61
	v_mfma_scale_f32_16x16x128_f8f6f4 v[138:141], v[250:255], v[44:49], v[138:141], v204, v204 op_sel_hi:[0,0,0] cbsz:2 blgp:2
	global_load_lds_dwordx4 v245, s[28:29]
	v_mfma_scale_f32_16x16x128_f8f6f4 v[134:137], v[180:185], v[38:43], v[134:137], v204, v204 op_sel_hi:[0,0,0] cbsz:2 blgp:2
	ds_read_b128 v[226:229], v205 offset:52224
	v_mfma_scale_f32_16x16x128_f8f6f4 v[130:133], v[250:255], v[38:43], v[130:133], v204, v204 op_sel_hi:[0,0,0] cbsz:2 blgp:2
	ds_read_b64 v[230:231], v206 offset:58880
	s_mov_b32 m0, s54
	v_mfma_scale_f32_16x16x128_f8f6f4 v[126:129], v[180:185], v[32:37], v[126:129], v204, v204 op_sel_hi:[0,0,0] cbsz:2 blgp:2
	global_load_lds_dwordx4 v246, s[34:35]
	v_mfma_scale_f32_16x16x128_f8f6f4 v[122:125], v[250:255], v[32:37], v[122:125], v204, v204 op_sel_hi:[0,0,0] cbsz:2 blgp:2
	v_mfma_scale_f32_16x16x128_f8f6f4 v[118:121], v[180:185], v[26:31], v[118:121], v204, v204 op_sel_hi:[0,0,0] cbsz:2 blgp:2
	v_mfma_scale_f32_16x16x128_f8f6f4 v[114:117], v[250:255], v[26:31], v[114:117], v204, v204 op_sel_hi:[0,0,0] cbsz:2 blgp:2
	s_waitcnt vmcnt(6)
	s_waitcnt lgkmcnt(0)
	s_barrier
	s_add_u32 s34, s30, 0x60000
	s_addc_u32 s35, s31, 0
	s_mov_b32 m0, s44
	v_mfma_scale_f32_16x16x128_f8f6f4 v[110:113], v[232:237], v[208:213], v[110:113], v204, v204 op_sel_hi:[0,0,0] cbsz:2 blgp:2
	global_load_lds_dwordx4 v246, s[34:35]
	ds_read_b128 v[44:47], v205
	v_mfma_scale_f32_16x16x128_f8f6f4 v[106:109], v[238:243], v[208:213], v[106:109], v204, v204 op_sel_hi:[0,0,0] cbsz:2 blgp:2
	ds_read_b64 v[48:49], v206 offset:8192
	ds_read_b128 v[38:41], v205 offset:1024
	v_mfma_scale_f32_16x16x128_f8f6f4 v[102:105], v[232:237], v[214:219], v[102:105], v204, v204 op_sel_hi:[0,0,0] cbsz:2 blgp:2
	ds_read_b64 v[42:43], v206 offset:8704
	ds_read_b128 v[32:35], v205 offset:2048
	v_mfma_scale_f32_16x16x128_f8f6f4 v[98:101], v[238:243], v[214:219], v[98:101], v204, v204 op_sel_hi:[0,0,0] cbsz:2 blgp:2
	ds_read_b64 v[36:37], v206 offset:9216
	ds_read_b128 v[26:29], v205 offset:3072
	v_mfma_scale_f32_16x16x128_f8f6f4 v[94:97], v[232:237], v[220:225], v[94:97], v204, v204 op_sel_hi:[0,0,0] cbsz:2 blgp:2
	ds_read_b64 v[30:31], v206 offset:9728
	ds_read_b128 v[20:23], v247
	v_mfma_scale_f32_16x16x128_f8f6f4 v[90:93], v[238:243], v[220:225], v[90:93], v204, v204 op_sel_hi:[0,0,0] cbsz:2 blgp:2
	ds_read_b64 v[24:25], v248
	ds_read_b128 v[14:17], v247 offset:1024
	v_mfma_scale_f32_16x16x128_f8f6f4 v[86:89], v[232:237], v[226:231], v[86:89], v204, v204 op_sel_hi:[0,0,0] cbsz:2 blgp:2
	ds_read_b64 v[18:19], v248 offset:512
	ds_read_b128 v[8:11], v247 offset:16384
	v_mfma_scale_f32_16x16x128_f8f6f4 v[82:85], v[238:243], v[226:231], v[82:85], v204, v204 op_sel_hi:[0,0,0] cbsz:2 blgp:2
	ds_read_b64 v[12:13], v248 offset:16384
	ds_read_b128 v[2:5], v247 offset:17408
	v_mfma_scale_f32_16x16x128_f8f6f4 v[78:81], v[180:185], v[208:213], v[78:81], v204, v204 op_sel_hi:[0,0,0] cbsz:2 blgp:2
	ds_read_b64 v[6:7], v248 offset:16896
	v_mfma_scale_f32_16x16x128_f8f6f4 v[74:77], v[250:255], v[208:213], v[74:77], v204, v204 op_sel_hi:[0,0,0] cbsz:2 blgp:2
	v_mfma_scale_f32_16x16x128_f8f6f4 v[70:73], v[180:185], v[214:219], v[70:73], v204, v204 op_sel_hi:[0,0,0] cbsz:2 blgp:2
	v_mfma_scale_f32_16x16x128_f8f6f4 v[66:69], v[250:255], v[214:219], v[66:69], v204, v204 op_sel_hi:[0,0,0] cbsz:2 blgp:2
	v_mfma_scale_f32_16x16x128_f8f6f4 v[62:65], v[180:185], v[220:225], v[62:65], v204, v204 op_sel_hi:[0,0,0] cbsz:2 blgp:2
	v_mfma_scale_f32_16x16x128_f8f6f4 v[58:61], v[250:255], v[220:225], v[58:61], v204, v204 op_sel_hi:[0,0,0] cbsz:2 blgp:2
	v_mfma_scale_f32_16x16x128_f8f6f4 v[54:57], v[180:185], v[226:231], v[54:57], v204, v204 op_sel_hi:[0,0,0] cbsz:2 blgp:2
	v_mfma_scale_f32_16x16x128_f8f6f4 v[50:53], v[250:255], v[226:231], v[50:53], v204, v204 op_sel_hi:[0,0,0] cbsz:2 blgp:2
	s_waitcnt vmcnt(6)
	s_waitcnt lgkmcnt(0)
	s_barrier
	s_add_i32 s73, s73, 2
	s_add_u32 s2, s2, 0x6000
	s_addc_u32 s3, s3, 0
	s_add_u32 s33, s33, 0x6000
	s_addc_u32 s72, s72, 0
	s_cmp_gt_u32 s73, 29
	s_cbranch_scc0 .Lsp1_top_L1
	s_mov_b32 s84, 1
	s_branch .LBB0_992

.Lg16_p_g1:
	s_cmp_eq_u32 s58, 31
	s_cselect_b32 s22, s52, s60
	s_cselect_b32 s23, s11, s61
	s_cselect_b32 s24, s54, s62
	s_cselect_b32 s25, s53, s63
	s_add_i32 m0, s35, 0x0
	v_mfma_f32_16x16x32_bf16 v[98:101], v[190:193], v[206:209], v[98:101]
	global_load_lds_dwordx4 v102, s[22:23]
	s_add_i32 m0, s35, 0x2000
	v_mfma_f32_16x16x32_bf16 v[98:101], v[194:197], v[210:213], v[98:101]
	global_load_lds_dwordx4 v104, s[22:23]
	s_add_i32 m0, s35, 0x10000
	v_mfma_f32_16x16x32_bf16 v[94:97], v[198:201], v[206:209], v[94:97]
	global_load_lds_dwordx4 v102, s[24:25]
	s_add_i32 m0, s35, 0x12000
	v_mfma_f32_16x16x32_bf16 v[94:97], v[202:205], v[210:213], v[94:97]
	global_load_lds_dwordx4 v104, s[24:25]
	ds_read_b128 v[206:209], v188 offset:16384
	ds_read_b128 v[210:213], v188 offset:17408
	v_mfma_f32_16x16x32_bf16 v[90:93], v[190:193], v[214:217], v[90:93]
	v_mfma_f32_16x16x32_bf16 v[90:93], v[194:197], v[218:221], v[90:93]
	v_mfma_f32_16x16x32_bf16 v[86:89], v[198:201], v[214:217], v[86:89]
	v_mfma_f32_16x16x32_bf16 v[86:89], v[202:205], v[218:221], v[86:89]
	ds_read_b128 v[214:217], v188 offset:18432
	ds_read_b128 v[218:221], v188 offset:19456
	v_mfma_f32_16x16x32_bf16 v[82:85], v[190:193], v[222:225], v[82:85]
	global_load_dwordx4 v[6:9], v186, s[84:85]
	v_mfma_f32_16x16x32_bf16 v[82:85], v[194:197], v[226:229], v[82:85]
	s_add_u32 s86, s84, 0xcc000
	s_addc_u32 s87, s85, 0
	global_load_dwordx4 v[10:13], v186, s[86:87]
	v_mfma_f32_16x16x32_bf16 v[78:81], v[198:201], v[222:225], v[78:81]
	s_add_u32 s86, s84, 0x198000
	s_addc_u32 s87, s85, 0
	global_load_dwordx4 v[14:17], v186, s[86:87]
	v_mfma_f32_16x16x32_bf16 v[78:81], v[202:205], v[226:229], v[78:81]
	ds_read_b128 v[222:225], v188 offset:20480
	ds_read_b128 v[226:229], v188 offset:21504
	s_add_u32 s86, s84, 0x264000
	s_addc_u32 s87, s85, 0
	global_load_dwordx4 v[18:21], v186, s[86:87]
	v_mfma_f32_16x16x32_bf16 v[74:77], v[190:193], v[230:233], v[74:77]
	s_add_u32 s86, s84, 0x660000
	s_addc_u32 s87, s85, 0
	global_load_dwordx4 v[22:25], v186, s[86:87]
	v_mfma_f32_16x16x32_bf16 v[74:77], v[194:197], v[234:237], v[74:77]
	s_add_u32 s86, s84, 0x72c000
	s_addc_u32 s87, s85, 0
	global_load_dwordx4 v[26:29], v186, s[86:87]
	v_mfma_f32_16x16x32_bf16 v[70:73], v[198:201], v[230:233], v[70:73]
	s_add_u32 s86, s84, 0x7f8000
	s_addc_u32 s87, s85, 0
	global_load_dwordx4 v[30:33], v186, s[86:87]
	v_mfma_f32_16x16x32_bf16 v[70:73], v[202:205], v[234:237], v[70:73]
	ds_read_b128 v[230:233], v188 offset:22528
	ds_read_b128 v[234:237], v188 offset:23552
	s_add_u32 s84, s84, 0x8c4000
	s_addc_u32 s85, s85, 0
	global_load_dwordx4 v[34:37], v186, s[84:85]
	s_waitcnt vmcnt(14)
	s_waitcnt lgkmcnt(0)
	s_barrier
	s_add_u32 s26, s22, 0x100000
	s_addc_u32 s27, s23, 0
	s_add_i32 m0, s35, 0x4000
	v_mfma_f32_16x16x32_bf16 v[66:69], v[190:193], v[206:209], v[66:69]
	global_load_lds_dwordx4 v102, s[26:27]
	v_mfma_f32_16x16x32_bf16 v[58:61], v[190:193], v[214:217], v[58:61]
	ds_read_b128 v[106:109], v187 offset:33792
	s_add_i32 m0, s35, 0x6000
	v_mfma_f32_16x16x32_bf16 v[50:53], v[190:193], v[222:225], v[50:53]
	global_load_lds_dwordx4 v104, s[26:27]
	v_mfma_f32_16x16x32_bf16 v[42:45], v[190:193], v[230:233], v[42:45]
	ds_read_b128 v[160:163], v187 offset:34816
	ds_read_b128 v[190:193], v187 offset:32768
	v_mfma_f32_16x16x32_bf16 v[66:69], v[194:197], v[210:213], v[66:69]
	ds_read_b128 v[250:253], v187 offset:35840
	v_mfma_f32_16x16x32_bf16 v[62:65], v[198:201], v[206:209], v[62:65]
	v_mfma_f32_16x16x32_bf16 v[62:65], v[202:205], v[210:213], v[62:65]
	ds_read_b128 v[206:209], v188 offset:32768
	ds_read_b128 v[210:213], v188 offset:33792
	v_mfma_f32_16x16x32_bf16 v[58:61], v[194:197], v[218:221], v[58:61]
	v_mfma_f32_16x16x32_bf16 v[54:57], v[198:201], v[214:217], v[54:57]
	v_mfma_f32_16x16x32_bf16 v[54:57], v[202:205], v[218:221], v[54:57]
	ds_read_b128 v[214:217], v188 offset:34816
	ds_read_b128 v[218:221], v188 offset:35840
	v_mfma_f32_16x16x32_bf16 v[50:53], v[194:197], v[226:229], v[50:53]
	v_mfma_f32_16x16x32_bf16 v[46:49], v[198:201], v[222:225], v[46:49]
	v_mfma_f32_16x16x32_bf16 v[46:49], v[202:205], v[226:229], v[46:49]
	ds_read_b128 v[222:225], v188 offset:36864
	ds_read_b128 v[226:229], v188 offset:37888
	v_mfma_f32_16x16x32_bf16 v[42:45], v[194:197], v[234:237], v[42:45]
	v_mfma_f32_16x16x32_bf16 v[38:41], v[198:201], v[230:233], v[38:41]
	v_mfma_f32_16x16x32_bf16 v[38:41], v[202:205], v[234:237], v[38:41]
	ds_read_b128 v[230:233], v188 offset:38912
	ds_read_b128 v[234:237], v188 offset:39936
	s_waitcnt vmcnt(14)
	s_waitcnt lgkmcnt(0)
	s_barrier
	s_add_u32 s22, s22, 0x4000
	s_addc_u32 s23, s23, 0
	s_add_u32 s24, s24, 0x4000
	s_addc_u32 s25, s25, 0
	s_add_i32 m0, s35, 0x8000
	v_mfma_f32_16x16x32_bf16 v[98:101], v[190:193], v[206:209], v[98:101]
	global_load_lds_dwordx4 v102, s[22:23]
	s_add_i32 m0, s35, 0xa000
	v_mfma_f32_16x16x32_bf16 v[98:101], v[106:109], v[210:213], v[98:101]
	global_load_lds_dwordx4 v104, s[22:23]
	s_add_i32 m0, s35, 0x18000
	v_mfma_f32_16x16x32_bf16 v[94:97], v[160:163], v[206:209], v[94:97]
	global_load_lds_dwordx4 v102, s[24:25]
	s_add_i32 m0, s35, 0x1a000
	v_mfma_f32_16x16x32_bf16 v[94:97], v[250:253], v[210:213], v[94:97]
	global_load_lds_dwordx4 v104, s[24:25]
	ds_read_b128 v[206:209], v188 offset:49152
	ds_read_b128 v[210:213], v188 offset:50176
	v_mfma_f32_16x16x32_bf16 v[90:93], v[190:193], v[214:217], v[90:93]
	v_mfma_f32_16x16x32_bf16 v[90:93], v[106:109], v[218:221], v[90:93]
	v_mfma_f32_16x16x32_bf16 v[86:89], v[160:163], v[214:217], v[86:89]
	v_mfma_f32_16x16x32_bf16 v[86:89], v[250:253], v[218:221], v[86:89]
	ds_read_b128 v[214:217], v188 offset:51200
	ds_read_b128 v[218:221], v188 offset:52224
	v_mfma_f32_16x16x32_bf16 v[82:85], v[190:193], v[222:225], v[82:85]
	v_mfma_f32_16x16x32_bf16 v[82:85], v[106:109], v[226:229], v[82:85]
	v_mfma_f32_16x16x32_bf16 v[78:81], v[160:163], v[222:225], v[78:81]
	v_mfma_f32_16x16x32_bf16 v[78:81], v[250:253], v[226:229], v[78:81]
	ds_read_b128 v[222:225], v188 offset:53248
	ds_read_b128 v[226:229], v188 offset:54272
	v_mfma_f32_16x16x32_bf16 v[74:77], v[190:193], v[230:233], v[74:77]
	v_mfma_f32_16x16x32_bf16 v[74:77], v[106:109], v[234:237], v[74:77]
	v_mfma_f32_16x16x32_bf16 v[70:73], v[160:163], v[230:233], v[70:73]
	v_mfma_f32_16x16x32_bf16 v[70:73], v[250:253], v[234:237], v[70:73]
	ds_read_b128 v[230:233], v188 offset:55296
	ds_read_b128 v[234:237], v188 offset:56320
	s_waitcnt vmcnt(14)
	s_waitcnt lgkmcnt(0)
	s_barrier
	s_add_u32 s26, s22, 0x100000
	s_addc_u32 s27, s23, 0
	s_add_i32 m0, s35, 0xc000
	v_mfma_f32_16x16x32_bf16 v[66:69], v[190:193], v[206:209], v[66:69]
	global_load_lds_dwordx4 v102, s[26:27]
	v_mfma_f32_16x16x32_bf16 v[58:61], v[190:193], v[214:217], v[58:61]
	ds_read_b128 v[194:197], v187 offset:1024
	s_add_i32 m0, s35, 0xe000
	v_mfma_f32_16x16x32_bf16 v[50:53], v[190:193], v[222:225], v[50:53]
	global_load_lds_dwordx4 v104, s[26:27]
	v_mfma_f32_16x16x32_bf16 v[42:45], v[190:193], v[230:233], v[42:45]
	ds_read_b128 v[198:201], v187 offset:2048
	ds_read_b128 v[190:193], v187
	v_mfma_f32_16x16x32_bf16 v[66:69], v[106:109], v[210:213], v[66:69]
	ds_read_b128 v[202:205], v187 offset:3072
	v_mfma_f32_16x16x32_bf16 v[62:65], v[160:163], v[206:209], v[62:65]
	v_mfma_f32_16x16x32_bf16 v[62:65], v[250:253], v[210:213], v[62:65]
	ds_read_b128 v[206:209], v188
	ds_read_b128 v[210:213], v188 offset:1024
	v_mfma_f32_16x16x32_bf16 v[58:61], v[106:109], v[218:221], v[58:61]
	v_mfma_f32_16x16x32_bf16 v[54:57], v[160:163], v[214:217], v[54:57]
	v_mfma_f32_16x16x32_bf16 v[54:57], v[250:253], v[218:221], v[54:57]
	ds_read_b128 v[214:217], v188 offset:2048
	ds_read_b128 v[218:221], v188 offset:3072
	v_mfma_f32_16x16x32_bf16 v[50:53], v[106:109], v[226:229], v[50:53]
	v_mfma_f32_16x16x32_bf16 v[46:49], v[160:163], v[222:225], v[46:49]
	v_mfma_f32_16x16x32_bf16 v[46:49], v[250:253], v[226:229], v[46:49]
	ds_read_b128 v[222:225], v188 offset:4096
	ds_read_b128 v[226:229], v188 offset:5120
	v_mfma_f32_16x16x32_bf16 v[42:45], v[106:109], v[234:237], v[42:45]
	v_mfma_f32_16x16x32_bf16 v[38:41], v[160:163], v[230:233], v[38:41]
	v_mfma_f32_16x16x32_bf16 v[38:41], v[250:253], v[234:237], v[38:41]
	ds_read_b128 v[230:233], v188 offset:6144
	ds_read_b128 v[234:237], v188 offset:7168
	s_waitcnt vmcnt(6)
	s_waitcnt lgkmcnt(0)
	s_barrier
	s_branch .Lg16_tail_g1
